# s5 Y-GEMM items: operand loads renamed into a 20-quad ring and issued many MFMAs ahead (was load, wait, MFMA for each of 136 MFMAs)
# baseline (speedup 1.0000x reference)
.LBB0_1514:
	s_ashr_i32 s0, s26, 1
	s_mul_hi_i32 s1, s0, 0x66666667
	s_lshr_b32 s16, s1, 31
	s_ashr_i32 s1, s1, 1
	s_add_i32 s1, s1, s16
	s_mul_i32 s16, s1, 5
	s_and_b32 s31, s1, 31
	s_sub_i32 s0, s0, s16
	s_ashr_i32 s30, s1, 5
	s_or_b32 s16, s8, s31
	s_mov_b32 s17, s9
	s_lshl_b32 s54, s0, 5
	s_lshl_b64 s[20:21], s[16:17], 17
	s_andn2_b64 vcc, exec, s[14:15]
	s_mul_i32 s27, s30, 0x810
	s_cbranch_vccnz .LBB0_1518
	v_mov_b32_e32 v0, v102
	s_movk_i32 s0, 0x81
	v_and_b32_e32 v6, 31, v0
	v_or_b32_e32 v81, s54, v6
	v_cmp_gt_i32_e32 vcc, s0, v81
	v_ashrrev_i32_e32 v80, 5, v0
	v_mov_b64_e32 v[2:3], s[6:7]
	v_cndmask_b32_e32 v0, 0, v81, vcc
	v_lshl_add_u32 v1, v0, 4, s27
	v_mad_i64_i32 v[2:3], s[0:1], v1, s44, v[2:3]
	s_lshl_b32 s0, s30, 5
	s_or_b32 s0, s0, s31
	v_ashrrev_i32_e32 v1, 31, v0
	v_mov_b32_e32 v7, 0xa0
	s_lshl_b64 s[18:19], s[16:17], 16
	s_lshl_b32 s38, s31, 4
	v_mad_i64_i32 v[0:1], s[0:1], s0, v7, v[0:1]
	v_lshlrev_b32_e32 v4, 3, v80
	s_add_u32 s0, s3, s20
	v_ashrrev_i32_e32 v5, 31, v4
	v_lshlrev_b64 v[0:1], 8, v[0:1]
	s_addc_u32 s1, s5, s21
	s_lshl_b32 s22, s31, 5
	s_mov_b32 s23, s39
	v_lshl_add_u64 v[72:73], s[12:13], 0, v[0:1]
	v_lshl_add_u64 v[0:1], v[2:3], 0, s[22:23]
	v_lshlrev_b64 v[74:75], 1, v[4:5]
	v_lshl_add_u64 v[70:71], v[0:1], 0, v[74:75]
	s_mov_b64 s[100:101], 0x1ec00000
	v_lshl_add_u64 v[200:201], v[70:71], 0, s[100:101]
	global_load_dwordx4 v[120:123], v[200:201], off offset:3584
	s_mov_b64 s[100:101], 0x1ec03000
	v_lshl_add_u64 v[200:201], v[70:71], 0, s[100:101]
	global_load_dwordx4 v[132:135], v[200:201], off offset:3584
	s_mov_b64 s[100:101], 0x1ec06000
	v_lshl_add_u64 v[200:201], v[70:71], 0, s[100:101]
	global_load_dwordx4 v[160:163], v[200:201], off offset:3584
	s_mov_b64 s[100:101], 0x1ec09000
	v_lshl_add_u64 v[200:201], v[70:71], 0, s[100:101]
	global_load_dwordx4 v[180:183], v[200:201], off offset:3584
	v_lshl_add_u64 v[4:5], s[0:1], 0, v[74:75]
	s_mov_b32 s0, 0x1ec00000
	v_lshlrev_b32_e32 v96, 8, v6
	v_add_co_u32_e64 v0, s[0:1], s0, v70
	v_lshlrev_b32_e32 v6, 9, v6
	v_mov_b32_e32 v7, v97
	v_addc_co_u32_e64 v1, s[0:1], 0, v71, s[0:1]
	v_lshl_add_u64 v[8:9], v[4:5], 0, v[6:7]
	s_mov_b64 s[100:101], 0xc000
	v_lshl_add_u64 v[200:201], v[8:9], 0, s[100:101]
	global_load_dwordx4 v[136:139], v[200:201], off
	s_mov_b64 s[100:101], 0xc000
	v_lshl_add_u64 v[200:201], v[8:9], 0, s[100:101]
	global_load_dwordx4 v[140:143], v[200:201], off offset:32
	s_mov_b64 s[100:101], 0x14000
	v_lshl_add_u64 v[200:201], v[8:9], 0, s[100:101]
	global_load_dwordx4 v[144:147], v[200:201], off
	s_mov_b64 s[100:101], 0x14000
	v_lshl_add_u64 v[200:201], v[8:9], 0, s[100:101]
	global_load_dwordx4 v[148:151], v[200:201], off offset:32
	s_mov_b64 s[100:101], 0x1c000
	v_lshl_add_u64 v[200:201], v[8:9], 0, s[100:101]
	global_load_dwordx4 v[152:155], v[200:201], off
	s_mov_b64 s[100:101], 0x1c000
	v_lshl_add_u64 v[200:201], v[8:9], 0, s[100:101]
	global_load_dwordx4 v[156:159], v[200:201], off offset:32
	v_add_co_u32_e64 v64, s[0:1], s52, v8
	s_nop 0
	v_addc_co_u32_e64 v65, s[0:1], 0, v9, s[0:1]
	global_load_dwordx4 v[124:127], v[64:65], off
	global_load_dwordx4 v[128:131], v[64:65], off offset:32
	global_load_dwordx4 v[164:167], v[64:65], off offset:64
	global_load_dwordx4 v[184:187], v[64:65], off offset:96
	s_mov_b32 s0, 0xc000
	s_nop 0
	v_add_co_u32_e64 v78, s[0:1], s0, v8
	s_nop 0
	v_addc_co_u32_e64 v79, s[0:1], 0, v9, s[0:1]
	global_load_dwordx4 v[168:171], v[78:79], off offset:64
	global_load_dwordx4 v[188:191], v[78:79], off offset:96
	s_mov_b32 s0, 0x14000
	s_nop 0
	v_add_co_u32_e64 v76, s[0:1], s0, v8
	s_nop 0
	v_addc_co_u32_e64 v77, s[0:1], 0, v9, s[0:1]
	global_load_dwordx4 v[172:175], v[76:77], off offset:64
	global_load_dwordx4 v[192:195], v[76:77], off offset:96
	s_mov_b32 s0, 0x1c000
	s_nop 0
	v_add_co_u32_e64 v68, s[0:1], s0, v8
	s_waitcnt vmcnt(17)
	v_cndmask_b32_e32 v123, 0, v123, vcc
	v_addc_co_u32_e64 v69, s[0:1], 0, v9, s[0:1]
	global_load_dwordx4 v[176:179], v[68:69], off offset:64
	global_load_dwordx4 v[196:199], v[68:69], off offset:96
	s_mov_b32 s0, 0x1ec03000
	s_nop 0
	v_add_co_u32_e64 v66, s[0:1], s0, v70
	v_cndmask_b32_e32 v122, 0, v122, vcc
	s_nop 0
	v_addc_co_u32_e64 v67, s[0:1], 0, v71, s[0:1]
	v_cndmask_b32_e32 v121, 0, v121, vcc
	v_cndmask_b32_e32 v120, 0, v120, vcc
	s_mov_b32 s0, 0x1ec06000
	v_add_co_u32_e64 v66, s[0:1], s0, v70
	s_waitcnt vmcnt(9)
	v_mfma_f32_32x32x16_bf16 v[48:63], v[124:127], v[120:123], 0
	s_mov_b64 s[100:101], 0x1ec0c000
	v_lshl_add_u64 v[200:201], v[70:71], 0, s[100:101]
	global_load_dwordx4 v[124:127], v[200:201], off offset:3584
	v_addc_co_u32_e64 v67, s[0:1], 0, v71, s[0:1]
	s_mov_b32 s0, 0x1ec09000
	s_waitcnt vmcnt(19)
	v_cndmask_b32_e32 v135, 0, v135, vcc
	v_cndmask_b32_e32 v134, 0, v134, vcc
	v_cndmask_b32_e32 v133, 0, v133, vcc
	v_cndmask_b32_e32 v132, 0, v132, vcc
	s_nop 1
	s_waitcnt vmcnt(9)
	v_mfma_f32_32x32x16_bf16 v[48:63], v[128:131], v[132:135], v[48:63]
	global_load_dwordx4 v[128:131], v[76:77], off offset:128
	s_waitcnt vmcnt(17)
	v_mfma_f32_32x32x16_bf16 v[32:47], v[136:139], v[120:123], 0
	global_load_dwordx4 v[136:139], v[78:79], off offset:160
	s_waitcnt vmcnt(17)
	v_mfma_f32_32x32x16_bf16 v[32:47], v[140:143], v[132:135], v[32:47]
	s_mov_b64 s[100:101], 0x1ec0f000
	v_lshl_add_u64 v[200:201], v[70:71], 0, s[100:101]
	global_load_dwordx4 v[140:143], v[200:201], off offset:3584
	s_waitcnt vmcnt(17)
	v_mfma_f32_32x32x16_bf16 v[16:31], v[144:147], v[120:123], 0
	global_load_dwordx4 v[144:147], v[76:77], off offset:160
	s_waitcnt vmcnt(17)
	v_mfma_f32_32x32x16_bf16 v[16:31], v[148:151], v[132:135], v[16:31]
	global_load_dwordx4 v[148:151], v[68:69], off offset:160
	s_waitcnt vmcnt(17)
	v_mfma_f32_32x32x16_bf16 v[0:15], v[152:155], v[120:123], 0
	global_load_dwordx4 v[120:123], v[78:79], off offset:128
	global_load_dwordx4 v[152:155], v[78:79], off offset:192
	s_waitcnt vmcnt(18)
	v_mfma_f32_32x32x16_bf16 v[0:15], v[156:159], v[132:135], v[0:15]
	global_load_dwordx4 v[132:135], v[68:69], off offset:128
	s_mov_b64 s[100:101], 0x1ec12000
	v_lshl_add_u64 v[200:201], v[70:71], 0, s[100:101]
	global_load_dwordx4 v[156:159], v[200:201], off offset:3584
	v_add_co_u32_e64 v66, s[0:1], s0, v70
	s_waitcnt vmcnt(27)
	v_cndmask_b32_e32 v163, 0, v163, vcc
	v_cndmask_b32_e32 v162, 0, v162, vcc
	v_cndmask_b32_e32 v161, 0, v161, vcc
	v_cndmask_b32_e32 v160, 0, v160, vcc
	v_addc_co_u32_e64 v67, s[0:1], 0, v71, s[0:1]
	s_waitcnt vmcnt(17)
	v_mfma_f32_32x32x16_bf16 v[48:63], v[164:167], v[160:163], v[48:63]
	global_load_dwordx4 v[164:167], v[68:69], off offset:192
	s_mov_b32 s0, 0x1ec0c000
	s_waitcnt vmcnt(16)
	v_mfma_f32_32x32x16_bf16 v[32:47], v[168:171], v[160:163], v[32:47]
	global_load_dwordx4 v[168:171], v[78:79], off offset:224
	s_waitcnt vmcnt(15)
	v_mfma_f32_32x32x16_bf16 v[16:31], v[172:175], v[160:163], v[16:31]
	s_mov_b64 s[100:101], 0x1ec15000
	v_lshl_add_u64 v[200:201], v[70:71], 0, s[100:101]
	global_load_dwordx4 v[172:175], v[200:201], off offset:3584
	s_waitcnt vmcnt(14)
	v_mfma_f32_32x32x16_bf16 v[0:15], v[176:179], v[160:163], v[0:15]
	global_load_dwordx4 v[160:163], v[76:77], off offset:192
	global_load_dwordx4 v[176:179], v[76:77], off offset:224
	s_waitcnt vmcnt(31)
	v_cndmask_b32_e32 v183, 0, v183, vcc
	v_cndmask_b32_e32 v182, 0, v182, vcc
	v_cndmask_b32_e32 v181, 0, v181, vcc
	v_cndmask_b32_e32 v180, 0, v180, vcc
	s_nop 0
	s_waitcnt vmcnt(21)
	v_mfma_f32_32x32x16_bf16 v[48:63], v[184:187], v[180:183], v[48:63]
	global_load_dwordx4 v[184:187], v[76:77], off offset:256
	s_waitcnt vmcnt(20)
	v_mfma_f32_32x32x16_bf16 v[32:47], v[188:191], v[180:183], v[32:47]
	s_mov_b64 s[100:101], 0x1ec18000
	v_lshl_add_u64 v[200:201], v[70:71], 0, s[100:101]
	global_load_dwordx4 v[188:191], v[200:201], off offset:3584
	s_waitcnt vmcnt(19)
	v_mfma_f32_32x32x16_bf16 v[16:31], v[192:195], v[180:183], v[16:31]
	global_load_dwordx4 v[192:195], v[68:69], off offset:256
	s_waitcnt vmcnt(18)
	v_mfma_f32_32x32x16_bf16 v[0:15], v[196:199], v[180:183], v[0:15]
	global_load_dwordx4 v[180:183], v[68:69], off offset:224
	global_load_dwordx4 v[196:199], v[76:77], off offset:288
	v_add_co_u32_e64 v64, s[0:1], s0, v70
	s_nop 0
	v_addc_co_u32_e64 v65, s[0:1], 0, v71, s[0:1]
	s_mov_b32 s0, 0x1ec0f000
	s_waitcnt vmcnt(19)
	v_cndmask_b32_e32 v127, 0, v127, vcc
	v_cndmask_b32_e32 v126, 0, v126, vcc
	v_cndmask_b32_e32 v125, 0, v125, vcc
	v_cndmask_b32_e32 v124, 0, v124, vcc
	s_nop 1
	s_waitcnt vmcnt(13)
	v_mfma_f32_32x32x16_bf16 v[32:47], v[120:123], v[124:127], v[32:47]
	s_mov_b64 s[100:101], 0x1ec1b000
	v_lshl_add_u64 v[200:201], v[70:71], 0, s[100:101]
	global_load_dwordx4 v[120:123], v[200:201], off offset:3584
	s_waitcnt vmcnt(19)
	v_mfma_f32_32x32x16_bf16 v[16:31], v[128:131], v[124:127], v[16:31]
	global_load_dwordx4 v[128:131], v[76:77], off offset:320
	s_waitcnt vmcnt(13)
	v_mfma_f32_32x32x16_bf16 v[0:15], v[132:135], v[124:127], v[0:15]
	global_load_dwordx4 v[124:127], v[68:69], off offset:288
	s_mov_b64 s[100:101], 0x1ec1e000
	v_lshl_add_u64 v[200:201], v[70:71], 0, s[100:101]
	global_load_dwordx4 v[132:135], v[200:201], off offset:3584
	v_add_co_u32_e64 v64, s[0:1], s0, v70
	s_nop 0
	v_addc_co_u32_e64 v65, s[0:1], 0, v71, s[0:1]
	s_mov_b32 s0, 0x1ec12000
	s_waitcnt vmcnt(20)
	v_cndmask_b32_e32 v143, 0, v143, vcc
	v_cndmask_b32_e32 v142, 0, v142, vcc
	v_cndmask_b32_e32 v141, 0, v141, vcc
	v_cndmask_b32_e32 v140, 0, v140, vcc
	s_nop 1
	s_waitcnt vmcnt(21)
	v_mfma_f32_32x32x16_bf16 v[32:47], v[136:139], v[140:143], v[32:47]
	global_load_dwordx4 v[136:139], v[76:77], off offset:352
	s_waitcnt vmcnt(20)
	v_mfma_f32_32x32x16_bf16 v[16:31], v[144:147], v[140:143], v[16:31]
	s_mov_b64 s[100:101], 0x1ec21000
	v_lshl_add_u64 v[200:201], v[70:71], 0, s[100:101]
	global_load_dwordx4 v[144:147], v[200:201], off offset:3584
	s_waitcnt vmcnt(20)
	v_mfma_f32_32x32x16_bf16 v[0:15], v[148:151], v[140:143], v[0:15]
	global_load_dwordx4 v[140:143], v[68:69], off offset:320
	global_load_dwordx4 v[148:151], v[68:69], off offset:352
	v_add_co_u32_e64 v64, s[0:1], s0, v70
	s_nop 0
	v_addc_co_u32_e64 v65, s[0:1], 0, v71, s[0:1]
	s_mov_b32 s0, 0x1ec15000
	s_waitcnt vmcnt(18)
	v_cndmask_b32_e32 v159, 0, v159, vcc
	v_cndmask_b32_e32 v158, 0, v158, vcc
	v_cndmask_b32_e32 v157, 0, v157, vcc
	v_cndmask_b32_e32 v156, 0, v156, vcc
	s_nop 1
	s_waitcnt vmcnt(20)
	v_mfma_f32_32x32x16_bf16 v[32:47], v[152:155], v[156:159], v[32:47]
	global_load_dwordx4 v[152:155], v[68:69], off offset:384
	s_waitcnt vmcnt(15)
	v_mfma_f32_32x32x16_bf16 v[16:31], v[160:163], v[156:159], v[16:31]
	global_load_dwordx4 v[160:163], v[68:69], off offset:416
	s_waitcnt vmcnt(19)
	v_mfma_f32_32x32x16_bf16 v[0:15], v[164:167], v[156:159], v[0:15]
	s_mov_b64 s[100:101], 0x1ec24000
	v_lshl_add_u64 v[200:201], v[70:71], 0, s[100:101]
	global_load_dwordx4 v[156:159], v[200:201], off offset:3584
	s_mov_b64 s[100:101], 0x1ec27000
	v_lshl_add_u64 v[200:201], v[70:71], 0, s[100:101]
	global_load_dwordx4 v[164:167], v[200:201], off offset:3584
	v_add_co_u32_e64 v64, s[0:1], s0, v70
	s_nop 0
	v_addc_co_u32_e64 v65, s[0:1], 0, v71, s[0:1]
	s_mov_b32 s0, 0x1ec18000
	s_waitcnt vmcnt(19)
	v_cndmask_b32_e32 v175, 0, v175, vcc
	v_cndmask_b32_e32 v174, 0, v174, vcc
	v_cndmask_b32_e32 v173, 0, v173, vcc
	v_cndmask_b32_e32 v172, 0, v172, vcc
	s_nop 1
	s_waitcnt vmcnt(20)
	v_mfma_f32_32x32x16_bf16 v[32:47], v[168:171], v[172:175], v[32:47]
	global_load_dwordx4 v[168:171], v[68:69], off offset:448
	s_waitcnt vmcnt(18)
	v_mfma_f32_32x32x16_bf16 v[16:31], v[176:179], v[172:175], v[16:31]
	s_mov_b64 s[100:101], 0x1ec2d000
	v_lshl_add_u64 v[200:201], v[70:71], 0, s[100:101]
	global_load_dwordx4 v[176:179], v[200:201], off offset:3584
	s_waitcnt vmcnt(15)
	v_mfma_f32_32x32x16_bf16 v[0:15], v[180:183], v[172:175], v[0:15]
	s_mov_b64 s[100:101], 0x1ec2a000
	v_lshl_add_u64 v[200:201], v[70:71], 0, s[100:101]
	global_load_dwordx4 v[172:175], v[200:201], off offset:3584
	global_load_dwordx4 v[180:183], v[68:69], off offset:480
	v_add_co_u32_e64 v64, s[0:1], s0, v70
	s_nop 0
	v_addc_co_u32_e64 v65, s[0:1], 0, v71, s[0:1]
	s_mov_b32 s0, 0x1ec1b000
	s_waitcnt vmcnt(19)
	v_cndmask_b32_e32 v191, 0, v191, vcc
	v_cndmask_b32_e32 v190, 0, v190, vcc
	v_cndmask_b32_e32 v189, 0, v189, vcc
	v_cndmask_b32_e32 v188, 0, v188, vcc
	s_nop 1
	s_waitcnt vmcnt(20)
	v_mfma_f32_32x32x16_bf16 v[16:31], v[184:187], v[188:191], v[16:31]
	s_waitcnt vmcnt(18)
	v_mfma_f32_32x32x16_bf16 v[0:15], v[192:195], v[188:191], v[0:15]
	v_add_co_u32_e64 v64, s[0:1], s0, v70
	s_nop 0
	v_addc_co_u32_e64 v65, s[0:1], 0, v71, s[0:1]
	s_mov_b32 s0, 0x1ec1e000
	s_waitcnt vmcnt(15)
	v_cndmask_b32_e32 v123, 0, v123, vcc
	v_cndmask_b32_e32 v122, 0, v122, vcc
	v_cndmask_b32_e32 v121, 0, v121, vcc
	v_cndmask_b32_e32 v120, 0, v120, vcc
	s_nop 1
	s_waitcnt vmcnt(16)
	v_mfma_f32_32x32x16_bf16 v[16:31], v[196:199], v[120:123], v[16:31]
	s_waitcnt vmcnt(13)
	v_mfma_f32_32x32x16_bf16 v[0:15], v[124:127], v[120:123], v[0:15]
	v_add_co_u32_e64 v64, s[0:1], s0, v70
	s_nop 0
	v_addc_co_u32_e64 v65, s[0:1], 0, v71, s[0:1]
	s_mov_b32 s0, 0x1ec21000
	s_waitcnt vmcnt(12)
	v_cndmask_b32_e32 v135, 0, v135, vcc
	v_cndmask_b32_e32 v134, 0, v134, vcc
	v_cndmask_b32_e32 v133, 0, v133, vcc
	v_cndmask_b32_e32 v132, 0, v132, vcc
	s_nop 1
	s_waitcnt vmcnt(14)
	v_mfma_f32_32x32x16_bf16 v[16:31], v[128:131], v[132:135], v[16:31]
	s_waitcnt vmcnt(9)
	v_mfma_f32_32x32x16_bf16 v[0:15], v[140:143], v[132:135], v[0:15]
	v_add_co_u32_e64 v64, s[0:1], s0, v70
	s_nop 1
	v_addc_co_u32_e64 v65, s[0:1], 0, v71, s[0:1]
	s_mov_b32 s0, 0x1ec24000
	s_waitcnt vmcnt(10)
	v_cndmask_b32_e32 v147, 0, v147, vcc
	v_cndmask_b32_e32 v146, 0, v146, vcc
	v_cndmask_b32_e32 v145, 0, v145, vcc
	v_cndmask_b32_e32 v144, 0, v144, vcc
	s_nop 1
	s_waitcnt vmcnt(11)
	v_mfma_f32_32x32x16_bf16 v[16:31], v[136:139], v[144:147], v[16:31]
	s_waitcnt vmcnt(8)
	v_mfma_f32_32x32x16_bf16 v[0:15], v[148:151], v[144:147], v[0:15]
	v_add_co_u32_e64 v64, s[0:1], s0, v70
	s_nop 0
	v_addc_co_u32_e64 v65, s[0:1], 0, v71, s[0:1]
	s_mov_b32 s0, 0x1ec27000
	s_waitcnt vmcnt(5)
	v_cndmask_b32_e32 v159, 0, v159, vcc
	v_cndmask_b32_e32 v158, 0, v158, vcc
	v_cndmask_b32_e32 v157, 0, v157, vcc
	v_cndmask_b32_e32 v156, 0, v156, vcc
	s_nop 1
	s_waitcnt vmcnt(7)
	v_mfma_f32_32x32x16_bf16 v[0:15], v[152:155], v[156:159], v[0:15]
	v_add_co_u32_e64 v64, s[0:1], s0, v70
	s_nop 0
	v_addc_co_u32_e64 v65, s[0:1], 0, v71, s[0:1]
	s_mov_b32 s0, 0x1ec2a000
	s_waitcnt vmcnt(4)
	v_cndmask_b32_e32 v167, 0, v167, vcc
	v_cndmask_b32_e32 v166, 0, v166, vcc
	v_cndmask_b32_e32 v165, 0, v165, vcc
	v_cndmask_b32_e32 v164, 0, v164, vcc
	s_nop 1
	s_waitcnt vmcnt(6)
	v_mfma_f32_32x32x16_bf16 v[0:15], v[160:163], v[164:167], v[0:15]
	v_add_co_u32_e64 v64, s[0:1], s0, v70
	s_nop 0
	v_addc_co_u32_e64 v65, s[0:1], 0, v71, s[0:1]
	s_mov_b32 s0, 0x1ec2d000
	s_waitcnt vmcnt(1)
	v_cndmask_b32_e32 v175, 0, v175, vcc
	v_cndmask_b32_e32 v174, 0, v174, vcc
	v_cndmask_b32_e32 v173, 0, v173, vcc
	v_cndmask_b32_e32 v172, 0, v172, vcc
	s_nop 1
	s_waitcnt vmcnt(3)
	v_mfma_f32_32x32x16_bf16 v[0:15], v[168:171], v[172:175], v[0:15]
	v_add_co_u32_e64 v64, s[0:1], s0, v70
	s_nop 1
	v_addc_co_u32_e64 v65, s[0:1], 0, v71, s[0:1]
	s_add_u32 s0, s6, s18
	s_addc_u32 s1, s7, s19
	s_mov_b64 s[18:19], 0
	s_waitcnt vmcnt(2)
	v_cndmask_b32_e32 v179, 0, v179, vcc
	v_cndmask_b32_e32 v178, 0, v178, vcc
	v_cndmask_b32_e32 v177, 0, v177, vcc
	v_cndmask_b32_e32 v176, 0, v176, vcc
	s_nop 0
	s_waitcnt vmcnt(0)
	v_mfma_f32_32x32x16_bf16 v[0:15], v[180:183], v[176:179], v[0:15]
	v_lshl_add_u64 v[70:71], v[72:73], 0, v[74:75]
	global_load_dwordx4 v[184:187], v[70:71], off
	global_load_dwordx4 v[124:127], v[70:71], off offset:32
	global_load_dwordx4 v[144:147], v[70:71], off offset:64
	global_load_dwordx4 v[164:167], v[70:71], off offset:96
	v_lshl_add_u64 v[68:69], s[0:1], 0, v[96:97]
	v_lshl_add_u64 v[74:75], v[68:69], 0, v[74:75]
	s_mov_b32 s0, 0x391f4000
	v_add_co_u32_e64 v72, s[0:1], s0, v74
	s_waitcnt vmcnt(3)
	v_cndmask_b32_e32 v79, 0, v187, vcc
	v_addc_co_u32_e64 v73, s[0:1], 0, v75, s[0:1]
	global_load_dwordx4 v[188:191], v[72:73], off
	global_load_dwordx4 v[128:131], v[72:73], off offset:32
	global_load_dwordx4 v[148:151], v[72:73], off offset:64
	global_load_dwordx4 v[168:171], v[72:73], off offset:96
	v_cndmask_b32_e32 v78, 0, v186, vcc
	v_cndmask_b32_e32 v77, 0, v185, vcc
	v_cndmask_b32_e32 v76, 0, v184, vcc
	global_load_dwordx4 v[184:187], v[70:71], off offset:128
	s_mov_b32 s0, 0x391f8000
	v_add_co_u32_e64 v68, s[0:1], s0, v74
	s_waitcnt vmcnt(4)
	v_mfma_f32_32x32x16_bf16 v[48:63], v[188:191], v[76:79], v[48:63]
	global_load_dwordx4 v[188:191], v[72:73], off offset:128
	v_addc_co_u32_e64 v69, s[0:1], 0, v75, s[0:1]
	global_load_dwordx4 v[192:195], v[68:69], off
	global_load_dwordx4 v[132:135], v[68:69], off offset:32
	global_load_dwordx4 v[152:155], v[68:69], off offset:64
	global_load_dwordx4 v[172:175], v[68:69], off offset:96
	s_mov_b32 s0, 0x391fc000
	s_waitcnt vmcnt(3)
	v_mfma_f32_32x32x16_bf16 v[32:47], v[192:195], v[76:79], v[32:47]
	global_load_dwordx4 v[192:195], v[68:69], off offset:128
	v_add_co_u32_e64 v66, s[0:1], s0, v74
	s_nop 1
	v_addc_co_u32_e64 v67, s[0:1], 0, v75, s[0:1]
	global_load_dwordx4 v[196:199], v[66:67], off
	global_load_dwordx4 v[136:139], v[66:67], off offset:32
	global_load_dwordx4 v[156:159], v[66:67], off offset:64
	global_load_dwordx4 v[176:179], v[66:67], off offset:96
	s_mov_b32 s0, 0x39200000
	v_add_co_u32_e64 v64, s[0:1], s0, v74
	s_waitcnt vmcnt(3)
	v_mfma_f32_32x32x16_bf16 v[16:31], v[196:199], v[76:79], v[16:31]
	global_load_dwordx4 v[196:199], v[66:67], off offset:128
	v_addc_co_u32_e64 v65, s[0:1], 0, v75, s[0:1]
	global_load_dwordx4 v[120:123], v[64:65], off
	global_load_dwordx4 v[140:143], v[64:65], off offset:32
	global_load_dwordx4 v[160:163], v[64:65], off offset:64
	global_load_dwordx4 v[180:183], v[64:65], off offset:96
	s_mov_b64 s[0:1], 0
	s_waitcnt vmcnt(3)
	v_mfma_f32_32x32x16_bf16 v[0:15], v[120:123], v[76:79], v[0:15]
	global_load_dwordx4 v[120:123], v[64:65], off offset:128
	s_waitcnt vmcnt(23)
	v_cndmask_b32_e32 v127, 0, v127, vcc
	v_cndmask_b32_e32 v126, 0, v126, vcc
	v_cndmask_b32_e32 v125, 0, v125, vcc
	v_cndmask_b32_e32 v124, 0, v124, vcc
	s_nop 0
	s_waitcnt vmcnt(19)
	v_mfma_f32_32x32x16_bf16 v[48:63], v[128:131], v[124:127], v[48:63]
	global_load_dwordx4 v[128:131], v[72:73], off offset:160
	s_waitcnt vmcnt(14)
	v_mfma_f32_32x32x16_bf16 v[32:47], v[132:135], v[124:127], v[32:47]
	global_load_dwordx4 v[132:135], v[68:69], off offset:160
	s_waitcnt vmcnt(10)
	v_mfma_f32_32x32x16_bf16 v[16:31], v[136:139], v[124:127], v[16:31]
	global_load_dwordx4 v[136:139], v[66:67], off offset:160
	s_waitcnt vmcnt(6)
	v_mfma_f32_32x32x16_bf16 v[0:15], v[140:143], v[124:127], v[0:15]
	global_load_dwordx4 v[124:127], v[70:71], off offset:160
	global_load_dwordx4 v[140:143], v[64:65], off offset:160
	s_waitcnt vmcnt(27)
	v_cndmask_b32_e32 v147, 0, v147, vcc
	v_cndmask_b32_e32 v146, 0, v146, vcc
	v_cndmask_b32_e32 v145, 0, v145, vcc
	v_cndmask_b32_e32 v144, 0, v144, vcc
	s_nop 0
	s_waitcnt vmcnt(23)
	v_mfma_f32_32x32x16_bf16 v[48:63], v[148:151], v[144:147], v[48:63]
	global_load_dwordx4 v[148:151], v[72:73], off offset:192
	s_waitcnt vmcnt(18)
	v_mfma_f32_32x32x16_bf16 v[32:47], v[152:155], v[144:147], v[32:47]
	global_load_dwordx4 v[152:155], v[68:69], off offset:192
	s_waitcnt vmcnt(14)
	v_mfma_f32_32x32x16_bf16 v[16:31], v[156:159], v[144:147], v[16:31]
	global_load_dwordx4 v[156:159], v[66:67], off offset:192
	s_waitcnt vmcnt(10)
	v_mfma_f32_32x32x16_bf16 v[0:15], v[160:163], v[144:147], v[0:15]
	global_load_dwordx4 v[144:147], v[70:71], off offset:192
	global_load_dwordx4 v[160:163], v[64:65], off offset:192
	s_waitcnt vmcnt(31)
	v_cndmask_b32_e32 v167, 0, v167, vcc
	v_cndmask_b32_e32 v166, 0, v166, vcc
	v_cndmask_b32_e32 v165, 0, v165, vcc
	v_cndmask_b32_e32 v164, 0, v164, vcc
	s_nop 0
	s_waitcnt vmcnt(27)
	v_mfma_f32_32x32x16_bf16 v[48:63], v[168:171], v[164:167], v[48:63]
	global_load_dwordx4 v[168:171], v[72:73], off offset:224
	s_waitcnt vmcnt(22)
	v_mfma_f32_32x32x16_bf16 v[32:47], v[172:175], v[164:167], v[32:47]
	global_load_dwordx4 v[172:175], v[68:69], off offset:224
	s_waitcnt vmcnt(18)
	v_mfma_f32_32x32x16_bf16 v[16:31], v[176:179], v[164:167], v[16:31]
	global_load_dwordx4 v[176:179], v[66:67], off offset:224
	s_waitcnt vmcnt(14)
	v_mfma_f32_32x32x16_bf16 v[0:15], v[180:183], v[164:167], v[0:15]
	global_load_dwordx4 v[164:167], v[70:71], off offset:224
	global_load_dwordx4 v[180:183], v[64:65], off offset:224
	s_waitcnt vmcnt(31)
	v_cndmask_b32_e32 v187, 0, v187, vcc
	v_cndmask_b32_e32 v186, 0, v186, vcc
	v_cndmask_b32_e32 v185, 0, v185, vcc
	v_cndmask_b32_e32 v184, 0, v184, vcc
	s_nop 0
	s_waitcnt vmcnt(30)
	v_mfma_f32_32x32x16_bf16 v[48:63], v[188:191], v[184:187], v[48:63]
	s_waitcnt vmcnt(25)
	v_mfma_f32_32x32x16_bf16 v[32:47], v[192:195], v[184:187], v[32:47]
	s_waitcnt vmcnt(20)
	v_mfma_f32_32x32x16_bf16 v[16:31], v[196:199], v[184:187], v[16:31]
	s_waitcnt vmcnt(15)
	v_mfma_f32_32x32x16_bf16 v[0:15], v[120:123], v[184:187], v[0:15]
	s_waitcnt vmcnt(11)
	v_cndmask_b32_e32 v127, 0, v127, vcc
	v_cndmask_b32_e32 v126, 0, v126, vcc
	v_cndmask_b32_e32 v125, 0, v125, vcc
	v_cndmask_b32_e32 v124, 0, v124, vcc
	s_nop 0
	s_waitcnt vmcnt(14)
	v_mfma_f32_32x32x16_bf16 v[48:63], v[128:131], v[124:127], v[48:63]
	s_waitcnt vmcnt(13)
	v_mfma_f32_32x32x16_bf16 v[32:47], v[132:135], v[124:127], v[32:47]
	s_waitcnt vmcnt(12)
	v_mfma_f32_32x32x16_bf16 v[16:31], v[136:139], v[124:127], v[16:31]
	s_waitcnt vmcnt(10)
	v_mfma_f32_32x32x16_bf16 v[0:15], v[140:143], v[124:127], v[0:15]
	s_waitcnt vmcnt(6)
	v_cndmask_b32_e32 v147, 0, v147, vcc
	v_cndmask_b32_e32 v146, 0, v146, vcc
	v_cndmask_b32_e32 v145, 0, v145, vcc
	v_cndmask_b32_e32 v144, 0, v144, vcc
	s_nop 0
	s_waitcnt vmcnt(9)
	v_mfma_f32_32x32x16_bf16 v[48:63], v[148:151], v[144:147], v[48:63]
	s_waitcnt vmcnt(8)
	v_mfma_f32_32x32x16_bf16 v[32:47], v[152:155], v[144:147], v[32:47]
	s_waitcnt vmcnt(7)
	v_mfma_f32_32x32x16_bf16 v[16:31], v[156:159], v[144:147], v[16:31]
	s_waitcnt vmcnt(5)
	v_mfma_f32_32x32x16_bf16 v[0:15], v[160:163], v[144:147], v[0:15]
	s_waitcnt vmcnt(1)
	v_cndmask_b32_e32 v167, 0, v167, vcc
	v_cndmask_b32_e32 v166, 0, v166, vcc
	v_cndmask_b32_e32 v165, 0, v165, vcc
	v_cndmask_b32_e32 v164, 0, v164, vcc
	s_nop 0
	s_waitcnt vmcnt(4)
	v_mfma_f32_32x32x16_bf16 v[48:63], v[168:171], v[164:167], v[48:63]
	s_waitcnt vmcnt(3)
	v_mfma_f32_32x32x16_bf16 v[32:47], v[172:175], v[164:167], v[32:47]
	s_waitcnt vmcnt(2)
	v_mfma_f32_32x32x16_bf16 v[16:31], v[176:179], v[164:167], v[16:31]
	s_waitcnt vmcnt(0)
	v_mfma_f32_32x32x16_bf16 v[0:15], v[180:183], v[164:167], v[0:15]
	s_and_saveexec_b64 s[22:23], vcc
	s_cbranch_execz .LBB0_1517
	s_nop 0
	v_mul_f32_e32 v65, 0x3d372713, v48
	v_mul_f32_e32 v65, v48, v65
	v_fma_f32 v65, v48, v65, v48
	v_mul_f32_e32 v65, 0xbfcc422a, v65
	v_mul_f32_e32 v65, 0x3fb8aa3b, v65
	v_exp_f32_e32 v65, v65
	v_lshl_add_u32 v70, v81, 4, s27
	v_or_b32_e32 v66, 2, v70
	v_ashrrev_i32_e32 v67, 31, v66
	v_add_f32_e32 v65, 1.0, v65
	v_rcp_f32_e32 v68, v65
	v_mul_f32_e32 v65, 0x3d372713, v49
	v_mul_f32_e32 v65, v49, v65
	v_fma_f32 v65, v49, v65, v49
	v_mul_f32_e32 v65, 0xbfcc422a, v65
	v_mul_f32_e32 v65, 0x3fb8aa3b, v65
	v_exp_f32_e32 v65, v65
	s_lshl_b32 s18, s38, 1
	v_lshlrev_b32_e32 v64, 2, v80
	s_add_u32 s18, s10, s18
	v_add_f32_e32 v65, 1.0, v65
	v_rcp_f32_e32 v69, v65
	s_addc_u32 s19, s11, 0
	v_ashrrev_i32_e32 v65, 31, v64
	v_pk_mul_f32 v[48:49], v[48:49], v[68:69]
	s_nop 0
	v_cvt_pk_bf16_f32 v68, v48, v49
	v_mul_f32_e32 v48, 0x3d372713, v50
	v_mul_f32_e32 v49, 0x3d372713, v51
	v_mul_f32_e32 v48, v50, v48
	v_mul_f32_e32 v49, v51, v49
	v_fma_f32 v48, v50, v48, v50
	v_fma_f32 v49, v51, v49, v51
	v_mul_f32_e32 v48, 0xbfcc422a, v48
	v_mul_f32_e32 v49, 0xbfcc422a, v49
	v_mul_f32_e32 v48, 0x3fb8aa3b, v48
	v_mul_f32_e32 v49, 0x3fb8aa3b, v49
	v_exp_f32_e32 v48, v48
	v_exp_f32_e32 v49, v49
	v_add_f32_e32 v48, 1.0, v48
	v_add_f32_e32 v49, 1.0, v49
	v_rcp_f32_e32 v48, v48
	v_rcp_f32_e32 v49, v49
	s_nop 0
	v_pk_mul_f32 v[48:49], v[50:51], v[48:49]
	s_nop 0
	v_cvt_pk_bf16_f32 v69, v48, v49
	v_lshlrev_b64 v[48:49], 10, v[66:67]
	v_mul_f32_e32 v67, 0x3d372713, v52
	v_mul_f32_e32 v67, v52, v67
	v_fma_f32 v67, v52, v67, v52
	v_mul_f32_e32 v67, 0xbfcc422a, v67
	v_mul_f32_e32 v67, 0x3fb8aa3b, v67
	v_exp_f32_e32 v67, v67
	v_lshl_add_u64 v[50:51], s[18:19], 0, v[48:49]
	v_lshlrev_b64 v[48:49], 1, v[64:65]
	v_lshl_add_u64 v[50:51], v[50:51], 0, v[48:49]
	v_add_f32_e32 v67, 1.0, v67
	global_store_dwordx2 v[50:51], v[68:69], off
	v_rcp_f32_e32 v68, v67
	v_mul_f32_e32 v67, 0x3d372713, v53
	v_mul_f32_e32 v67, v53, v67
	v_fma_f32 v67, v53, v67, v53
	v_mul_f32_e32 v67, 0xbfcc422a, v67
	v_mul_f32_e32 v67, 0x3fb8aa3b, v67
	v_exp_f32_e32 v67, v67
	v_add_u32_e32 v66, 8, v64
	v_add_f32_e32 v67, 1.0, v67
	v_rcp_f32_e32 v69, v67
	v_ashrrev_i32_e32 v67, 31, v66
	v_pk_mul_f32 v[52:53], v[52:53], v[68:69]
	s_nop 0
	v_cvt_pk_bf16_f32 v52, v52, v53
	v_mul_f32_e32 v53, 0x3d372713, v54
	v_mul_f32_e32 v53, v54, v53
	v_fma_f32 v53, v54, v53, v54
	v_mul_f32_e32 v53, 0xbfcc422a, v53
	v_mul_f32_e32 v53, 0x3fb8aa3b, v53
	v_exp_f32_e32 v53, v53
	s_nop 0
	v_add_f32_e32 v53, 1.0, v53
	v_rcp_f32_e32 v68, v53
	v_mul_f32_e32 v53, 0x3d372713, v55
	v_mul_f32_e32 v53, v55, v53
	v_fma_f32 v53, v55, v53, v55
	v_mul_f32_e32 v53, 0xbfcc422a, v53
	v_mul_f32_e32 v53, 0x3fb8aa3b, v53
	v_exp_f32_e32 v53, v53
	s_nop 0
	v_add_f32_e32 v53, 1.0, v53
	v_rcp_f32_e32 v69, v53
	s_nop 0
	v_pk_mul_f32 v[54:55], v[54:55], v[68:69]
	s_nop 0
	v_cvt_pk_bf16_f32 v53, v54, v55
	global_store_dwordx2 v[50:51], v[52:53], off offset:16
	v_mul_f32_e32 v50, 0x3d372713, v56
	v_mul_f32_e32 v51, 0x3d372713, v57
	v_mul_f32_e32 v50, v56, v50
	v_mul_f32_e32 v51, v57, v51
	v_fma_f32 v50, v56, v50, v56
	v_fma_f32 v51, v57, v51, v57
	v_mul_f32_e32 v50, 0xbfcc422a, v50
	v_mul_f32_e32 v51, 0xbfcc422a, v51
	v_mul_f32_e32 v50, 0x3fb8aa3b, v50
	v_mul_f32_e32 v51, 0x3fb8aa3b, v51
	v_exp_f32_e32 v50, v50
	v_exp_f32_e32 v51, v51
	v_add_f32_e32 v50, 1.0, v50
	v_add_f32_e32 v51, 1.0, v51
	v_rcp_f32_e32 v50, v50
	v_rcp_f32_e32 v51, v51
	s_nop 0
	v_pk_mul_f32 v[50:51], v[56:57], v[50:51]
	s_nop 0
	v_cvt_pk_bf16_f32 v50, v50, v51
	v_mul_f32_e32 v51, 0x3d372713, v58
	v_mul_f32_e32 v51, v58, v51
	v_fma_f32 v51, v58, v51, v58
	v_mul_f32_e32 v51, 0xbfcc422a, v51
	v_mul_f32_e32 v51, 0x3fb8aa3b, v51
	v_exp_f32_e32 v51, v51
	s_nop 0
	v_add_f32_e32 v51, 1.0, v51
	v_rcp_f32_e32 v52, v51
	v_mul_f32_e32 v51, 0x3d372713, v59
	v_mul_f32_e32 v51, v59, v51
	v_fma_f32 v51, v59, v51, v59
	v_mul_f32_e32 v51, 0xbfcc422a, v51
	v_mul_f32_e32 v51, 0x3fb8aa3b, v51
	v_exp_f32_e32 v51, v51
	s_nop 0
	v_add_f32_e32 v51, 1.0, v51
	v_rcp_f32_e32 v53, v51
	s_nop 0
	v_pk_mul_f32 v[52:53], v[58:59], v[52:53]
	s_nop 0
	v_cvt_pk_bf16_f32 v51, v52, v53
	v_or_b32_e32 v52, 3, v70
	v_ashrrev_i32_e32 v53, 31, v52
	v_lshlrev_b64 v[52:53], 10, v[52:53]
	v_lshl_add_u64 v[52:53], s[18:19], 0, v[52:53]
	v_lshl_add_u64 v[52:53], v[52:53], 0, v[48:49]
	global_store_dwordx2 v[52:53], v[50:51], off
	v_mul_f32_e32 v50, 0x3d372713, v60
	v_mul_f32_e32 v51, 0x3d372713, v61
	v_mul_f32_e32 v50, v60, v50
	v_mul_f32_e32 v51, v61, v51
	v_fma_f32 v50, v60, v50, v60
	v_fma_f32 v51, v61, v51, v61
	v_mul_f32_e32 v50, 0xbfcc422a, v50
	v_mul_f32_e32 v51, 0xbfcc422a, v51
	v_mul_f32_e32 v50, 0x3fb8aa3b, v50
	v_mul_f32_e32 v51, 0x3fb8aa3b, v51
	v_exp_f32_e32 v50, v50
	v_exp_f32_e32 v51, v51
	v_add_f32_e32 v50, 1.0, v50
	v_add_f32_e32 v51, 1.0, v51
	v_rcp_f32_e32 v50, v50
	v_rcp_f32_e32 v51, v51
	s_nop 0
	v_pk_mul_f32 v[50:51], v[60:61], v[50:51]
	s_nop 0
	v_cvt_pk_bf16_f32 v50, v50, v51
	v_mul_f32_e32 v51, 0x3d372713, v62
	v_mul_f32_e32 v51, v62, v51
	v_fma_f32 v51, v62, v51, v62
	v_mul_f32_e32 v51, 0xbfcc422a, v51
	v_mul_f32_e32 v51, 0x3fb8aa3b, v51
	v_exp_f32_e32 v51, v51
	s_nop 0
	v_add_f32_e32 v51, 1.0, v51
	v_rcp_f32_e32 v54, v51
	v_mul_f32_e32 v51, 0x3d372713, v63
	v_mul_f32_e32 v51, v63, v51
	v_fma_f32 v51, v63, v51, v63
	v_mul_f32_e32 v51, 0xbfcc422a, v51
	v_mul_f32_e32 v51, 0x3fb8aa3b, v51
	v_exp_f32_e32 v51, v51
	s_nop 0
	v_add_f32_e32 v51, 1.0, v51
	v_rcp_f32_e32 v55, v51
	s_nop 0
	v_pk_mul_f32 v[54:55], v[62:63], v[54:55]
	s_nop 0
	v_cvt_pk_bf16_f32 v51, v54, v55
	global_store_dwordx2 v[52:53], v[50:51], off offset:16
	v_mul_f32_e32 v51, 0x3d372713, v32
	v_mul_f32_e32 v51, v32, v51
	v_fma_f32 v51, v32, v51, v32
	v_mul_f32_e32 v51, 0xbfcc422a, v51
	v_mul_f32_e32 v51, 0x3fb8aa3b, v51
	v_exp_f32_e32 v51, v51
	v_or_b32_e32 v50, 6, v70
	v_add_f32_e32 v51, 1.0, v51
	v_rcp_f32_e32 v52, v51
	v_mul_f32_e32 v51, 0x3d372713, v33
	v_mul_f32_e32 v51, v33, v51
	v_fma_f32 v51, v33, v51, v33
	v_mul_f32_e32 v51, 0xbfcc422a, v51
	v_mul_f32_e32 v51, 0x3fb8aa3b, v51
	v_exp_f32_e32 v51, v51
	s_nop 0
	v_add_f32_e32 v51, 1.0, v51
	v_rcp_f32_e32 v53, v51
	v_ashrrev_i32_e32 v51, 31, v50
	v_pk_mul_f32 v[32:33], v[32:33], v[52:53]
	s_nop 0
	v_cvt_pk_bf16_f32 v32, v32, v33
	v_mul_f32_e32 v33, 0x3d372713, v34
	v_mul_f32_e32 v33, v34, v33
	v_fma_f32 v33, v34, v33, v34
	v_mul_f32_e32 v33, 0xbfcc422a, v33
	v_mul_f32_e32 v33, 0x3fb8aa3b, v33
	v_exp_f32_e32 v33, v33
	s_nop 0
	v_add_f32_e32 v33, 1.0, v33
	v_rcp_f32_e32 v52, v33
	v_mul_f32_e32 v33, 0x3d372713, v35
	v_mul_f32_e32 v33, v35, v33
	v_fma_f32 v33, v35, v33, v35
	v_mul_f32_e32 v33, 0xbfcc422a, v33
	v_mul_f32_e32 v33, 0x3fb8aa3b, v33
	v_exp_f32_e32 v33, v33
	s_nop 0
	v_add_f32_e32 v33, 1.0, v33
	v_rcp_f32_e32 v53, v33
	s_nop 0
	v_pk_mul_f32 v[34:35], v[34:35], v[52:53]
	s_nop 0
	v_cvt_pk_bf16_f32 v33, v34, v35
	v_lshlrev_b64 v[34:35], 10, v[50:51]
	v_lshl_add_u64 v[34:35], s[18:19], 0, v[34:35]
	v_lshl_add_u64 v[34:35], v[34:35], 0, v[48:49]
	global_store_dwordx2 v[34:35], v[32:33], off
	v_mul_f32_e32 v32, 0x3d372713, v36
	v_mul_f32_e32 v33, 0x3d372713, v37
	v_mul_f32_e32 v32, v36, v32
	v_mul_f32_e32 v33, v37, v33
	v_fma_f32 v32, v36, v32, v36
	v_fma_f32 v33, v37, v33, v37
	v_mul_f32_e32 v32, 0xbfcc422a, v32
	v_mul_f32_e32 v33, 0xbfcc422a, v33
	v_mul_f32_e32 v32, 0x3fb8aa3b, v32
	v_mul_f32_e32 v33, 0x3fb8aa3b, v33
	v_exp_f32_e32 v32, v32
	v_exp_f32_e32 v33, v33
	v_add_f32_e32 v32, 1.0, v32
	v_add_f32_e32 v33, 1.0, v33
	v_rcp_f32_e32 v32, v32
	v_rcp_f32_e32 v33, v33
	s_nop 0
	v_pk_mul_f32 v[32:33], v[36:37], v[32:33]
	s_nop 0
	v_cvt_pk_bf16_f32 v32, v32, v33
	v_mul_f32_e32 v33, 0x3d372713, v38
	v_mul_f32_e32 v33, v38, v33
	v_fma_f32 v33, v38, v33, v38
	v_mul_f32_e32 v33, 0xbfcc422a, v33
	v_mul_f32_e32 v33, 0x3fb8aa3b, v33
	v_exp_f32_e32 v33, v33
	s_nop 0
	v_add_f32_e32 v33, 1.0, v33
	v_rcp_f32_e32 v36, v33
	v_mul_f32_e32 v33, 0x3d372713, v39
	v_mul_f32_e32 v33, v39, v33
	v_fma_f32 v33, v39, v33, v39
	v_mul_f32_e32 v33, 0xbfcc422a, v33
	v_mul_f32_e32 v33, 0x3fb8aa3b, v33
	v_exp_f32_e32 v33, v33
	s_nop 0
	v_add_f32_e32 v33, 1.0, v33
	v_rcp_f32_e32 v37, v33
	s_nop 0
	v_pk_mul_f32 v[36:37], v[38:39], v[36:37]
	s_nop 0
	v_cvt_pk_bf16_f32 v33, v36, v37
	global_store_dwordx2 v[34:35], v[32:33], off offset:16
	v_mul_f32_e32 v32, 0x3d372713, v40
	v_mul_f32_e32 v33, 0x3d372713, v41
	v_mul_f32_e32 v32, v40, v32
	v_mul_f32_e32 v33, v41, v33
	v_fma_f32 v32, v40, v32, v40
	v_fma_f32 v33, v41, v33, v41
	v_mul_f32_e32 v32, 0xbfcc422a, v32
	v_mul_f32_e32 v33, 0xbfcc422a, v33
	v_mul_f32_e32 v32, 0x3fb8aa3b, v32
	v_mul_f32_e32 v33, 0x3fb8aa3b, v33
	v_exp_f32_e32 v32, v32
	v_exp_f32_e32 v33, v33
	v_add_f32_e32 v32, 1.0, v32
	v_add_f32_e32 v33, 1.0, v33
	v_rcp_f32_e32 v32, v32
	v_rcp_f32_e32 v33, v33
	s_nop 0
	v_pk_mul_f32 v[32:33], v[40:41], v[32:33]
	s_nop 0
	v_cvt_pk_bf16_f32 v32, v32, v33
	v_mul_f32_e32 v33, 0x3d372713, v42
	v_mul_f32_e32 v33, v42, v33
	v_fma_f32 v33, v42, v33, v42
	v_mul_f32_e32 v33, 0xbfcc422a, v33
	v_mul_f32_e32 v33, 0x3fb8aa3b, v33
	v_exp_f32_e32 v33, v33
	s_nop 0
	v_add_f32_e32 v33, 1.0, v33
	v_rcp_f32_e32 v34, v33
	v_mul_f32_e32 v33, 0x3d372713, v43
	v_mul_f32_e32 v33, v43, v33
	v_fma_f32 v33, v43, v33, v43
	v_mul_f32_e32 v33, 0xbfcc422a, v33
	v_mul_f32_e32 v33, 0x3fb8aa3b, v33
	v_exp_f32_e32 v33, v33
	s_nop 0
	v_add_f32_e32 v33, 1.0, v33
	v_rcp_f32_e32 v35, v33
	s_nop 0
	v_pk_mul_f32 v[34:35], v[42:43], v[34:35]
	s_nop 0
	v_cvt_pk_bf16_f32 v33, v34, v35
	v_or_b32_e32 v34, 7, v70
	v_ashrrev_i32_e32 v35, 31, v34
	v_lshlrev_b64 v[34:35], 10, v[34:35]
	v_lshl_add_u64 v[34:35], s[18:19], 0, v[34:35]
	v_lshl_add_u64 v[34:35], v[34:35], 0, v[48:49]
	global_store_dwordx2 v[34:35], v[32:33], off
	v_mul_f32_e32 v32, 0x3d372713, v44
	v_mul_f32_e32 v33, 0x3d372713, v45
	v_mul_f32_e32 v32, v44, v32
	v_mul_f32_e32 v33, v45, v33
	v_fma_f32 v32, v44, v32, v44
	v_fma_f32 v33, v45, v33, v45
	v_mul_f32_e32 v32, 0xbfcc422a, v32
	v_mul_f32_e32 v33, 0xbfcc422a, v33
	v_mul_f32_e32 v32, 0x3fb8aa3b, v32
	v_mul_f32_e32 v33, 0x3fb8aa3b, v33
	v_exp_f32_e32 v32, v32
	v_exp_f32_e32 v33, v33
	v_add_f32_e32 v32, 1.0, v32
	v_add_f32_e32 v33, 1.0, v33
	v_rcp_f32_e32 v32, v32
	v_rcp_f32_e32 v33, v33
	s_nop 0
	v_pk_mul_f32 v[32:33], v[44:45], v[32:33]
	s_nop 0
	v_cvt_pk_bf16_f32 v32, v32, v33
	v_mul_f32_e32 v33, 0x3d372713, v46
	v_mul_f32_e32 v33, v46, v33
	v_fma_f32 v33, v46, v33, v46
	v_mul_f32_e32 v33, 0xbfcc422a, v33
	v_mul_f32_e32 v33, 0x3fb8aa3b, v33
	v_exp_f32_e32 v33, v33
	s_nop 0
	v_add_f32_e32 v33, 1.0, v33
	v_rcp_f32_e32 v36, v33
	v_mul_f32_e32 v33, 0x3d372713, v47
	v_mul_f32_e32 v33, v47, v33
	v_fma_f32 v33, v47, v33, v47
	v_mul_f32_e32 v33, 0xbfcc422a, v33
	v_mul_f32_e32 v33, 0x3fb8aa3b, v33
	v_exp_f32_e32 v33, v33
	s_nop 0
	v_add_f32_e32 v33, 1.0, v33
	v_rcp_f32_e32 v37, v33
	s_nop 0
	v_pk_mul_f32 v[36:37], v[46:47], v[36:37]
	s_nop 0
	v_cvt_pk_bf16_f32 v33, v36, v37
	global_store_dwordx2 v[34:35], v[32:33], off offset:16
	v_mul_f32_e32 v33, 0x3d372713, v16
	v_mul_f32_e32 v33, v16, v33
	v_fma_f32 v33, v16, v33, v16
	v_mul_f32_e32 v33, 0xbfcc422a, v33
	v_mul_f32_e32 v33, 0x3fb8aa3b, v33
	v_exp_f32_e32 v33, v33
	v_or_b32_e32 v32, 10, v70
	v_add_f32_e32 v33, 1.0, v33
	v_rcp_f32_e32 v34, v33
	v_mul_f32_e32 v33, 0x3d372713, v17
	v_mul_f32_e32 v33, v17, v33
	v_fma_f32 v33, v17, v33, v17
	v_mul_f32_e32 v33, 0xbfcc422a, v33
	v_mul_f32_e32 v33, 0x3fb8aa3b, v33
	v_exp_f32_e32 v33, v33
	s_nop 0
	v_add_f32_e32 v33, 1.0, v33
	v_rcp_f32_e32 v35, v33
	v_ashrrev_i32_e32 v33, 31, v32
	v_pk_mul_f32 v[16:17], v[16:17], v[34:35]
	s_nop 0
	v_cvt_pk_bf16_f32 v16, v16, v17
	v_mul_f32_e32 v17, 0x3d372713, v18
	v_mul_f32_e32 v17, v18, v17
	v_fma_f32 v17, v18, v17, v18
	v_mul_f32_e32 v17, 0xbfcc422a, v17
	v_mul_f32_e32 v17, 0x3fb8aa3b, v17
	v_exp_f32_e32 v17, v17
	s_nop 0
	v_add_f32_e32 v17, 1.0, v17
	v_rcp_f32_e32 v34, v17
	v_mul_f32_e32 v17, 0x3d372713, v19
	v_mul_f32_e32 v17, v19, v17
	v_fma_f32 v17, v19, v17, v19
	v_mul_f32_e32 v17, 0xbfcc422a, v17
	v_mul_f32_e32 v17, 0x3fb8aa3b, v17
	v_exp_f32_e32 v17, v17
	s_nop 0
	v_add_f32_e32 v17, 1.0, v17
	v_rcp_f32_e32 v35, v17
	s_nop 0
	v_pk_mul_f32 v[18:19], v[18:19], v[34:35]
	s_nop 0
	v_cvt_pk_bf16_f32 v17, v18, v19
	v_lshlrev_b64 v[18:19], 10, v[32:33]
	v_lshl_add_u64 v[18:19], s[18:19], 0, v[18:19]
	v_lshl_add_u64 v[18:19], v[18:19], 0, v[48:49]
	global_store_dwordx2 v[18:19], v[16:17], off
	v_mul_f32_e32 v16, 0x3d372713, v20
	v_mul_f32_e32 v17, 0x3d372713, v21
	v_mul_f32_e32 v16, v20, v16
	v_mul_f32_e32 v17, v21, v17
	v_fma_f32 v16, v20, v16, v20
	v_fma_f32 v17, v21, v17, v21
	v_mul_f32_e32 v16, 0xbfcc422a, v16
	v_mul_f32_e32 v17, 0xbfcc422a, v17
	v_mul_f32_e32 v16, 0x3fb8aa3b, v16
	v_mul_f32_e32 v17, 0x3fb8aa3b, v17
	v_exp_f32_e32 v16, v16
	v_exp_f32_e32 v17, v17
	v_add_f32_e32 v16, 1.0, v16
	v_add_f32_e32 v17, 1.0, v17
	v_rcp_f32_e32 v16, v16
	v_rcp_f32_e32 v17, v17
	s_nop 0
	v_pk_mul_f32 v[16:17], v[20:21], v[16:17]
	s_nop 0
	v_cvt_pk_bf16_f32 v16, v16, v17
	v_mul_f32_e32 v17, 0x3d372713, v22
	v_mul_f32_e32 v17, v22, v17
	v_fma_f32 v17, v22, v17, v22
	v_mul_f32_e32 v17, 0xbfcc422a, v17
	v_mul_f32_e32 v17, 0x3fb8aa3b, v17
	v_exp_f32_e32 v17, v17
	s_nop 0
	v_add_f32_e32 v17, 1.0, v17
	v_rcp_f32_e32 v20, v17
	v_mul_f32_e32 v17, 0x3d372713, v23
	v_mul_f32_e32 v17, v23, v17
	v_fma_f32 v17, v23, v17, v23
	v_mul_f32_e32 v17, 0xbfcc422a, v17
	v_mul_f32_e32 v17, 0x3fb8aa3b, v17
	v_exp_f32_e32 v17, v17
	s_nop 0
	v_add_f32_e32 v17, 1.0, v17
	v_rcp_f32_e32 v21, v17
	s_nop 0
	v_pk_mul_f32 v[20:21], v[22:23], v[20:21]
	s_nop 0
	v_cvt_pk_bf16_f32 v17, v20, v21
	global_store_dwordx2 v[18:19], v[16:17], off offset:16
	v_mul_f32_e32 v16, 0x3d372713, v24
	v_mul_f32_e32 v17, 0x3d372713, v25
	v_mul_f32_e32 v16, v24, v16
	v_mul_f32_e32 v17, v25, v17
	v_fma_f32 v16, v24, v16, v24
	v_fma_f32 v17, v25, v17, v25
	v_mul_f32_e32 v16, 0xbfcc422a, v16
	v_mul_f32_e32 v17, 0xbfcc422a, v17
	v_mul_f32_e32 v16, 0x3fb8aa3b, v16
	v_mul_f32_e32 v17, 0x3fb8aa3b, v17
	v_exp_f32_e32 v16, v16
	v_exp_f32_e32 v17, v17
	v_add_f32_e32 v16, 1.0, v16
	v_add_f32_e32 v17, 1.0, v17
	v_rcp_f32_e32 v16, v16
	v_rcp_f32_e32 v17, v17
	s_nop 0
	v_pk_mul_f32 v[16:17], v[24:25], v[16:17]
	s_nop 0
	v_cvt_pk_bf16_f32 v16, v16, v17
	v_mul_f32_e32 v17, 0x3d372713, v26
	v_mul_f32_e32 v17, v26, v17
	v_fma_f32 v17, v26, v17, v26
	v_mul_f32_e32 v17, 0xbfcc422a, v17
	v_mul_f32_e32 v17, 0x3fb8aa3b, v17
	v_exp_f32_e32 v17, v17
	s_nop 0
	v_add_f32_e32 v17, 1.0, v17
	v_rcp_f32_e32 v18, v17
	v_mul_f32_e32 v17, 0x3d372713, v27
	v_mul_f32_e32 v17, v27, v17
	v_fma_f32 v17, v27, v17, v27
	v_mul_f32_e32 v17, 0xbfcc422a, v17
	v_mul_f32_e32 v17, 0x3fb8aa3b, v17
	v_exp_f32_e32 v17, v17
	s_nop 0
	v_add_f32_e32 v17, 1.0, v17
	v_rcp_f32_e32 v19, v17
	s_nop 0
	v_pk_mul_f32 v[18:19], v[26:27], v[18:19]
	s_nop 0
	v_cvt_pk_bf16_f32 v17, v18, v19
	v_or_b32_e32 v18, 11, v70
	v_ashrrev_i32_e32 v19, 31, v18
	v_lshlrev_b64 v[18:19], 10, v[18:19]
	v_lshl_add_u64 v[18:19], s[18:19], 0, v[18:19]
	v_lshl_add_u64 v[18:19], v[18:19], 0, v[48:49]
	global_store_dwordx2 v[18:19], v[16:17], off
	v_mul_f32_e32 v16, 0x3d372713, v28
	v_mul_f32_e32 v17, 0x3d372713, v29
	v_mul_f32_e32 v16, v28, v16
	v_mul_f32_e32 v17, v29, v17
	v_fma_f32 v16, v28, v16, v28
	v_fma_f32 v17, v29, v17, v29
	v_mul_f32_e32 v16, 0xbfcc422a, v16
	v_mul_f32_e32 v17, 0xbfcc422a, v17
	v_mul_f32_e32 v16, 0x3fb8aa3b, v16
	v_mul_f32_e32 v17, 0x3fb8aa3b, v17
	v_exp_f32_e32 v16, v16
	v_exp_f32_e32 v17, v17
	v_add_f32_e32 v16, 1.0, v16
	v_add_f32_e32 v17, 1.0, v17
	v_rcp_f32_e32 v16, v16
	v_rcp_f32_e32 v17, v17
	s_nop 0
	v_pk_mul_f32 v[16:17], v[28:29], v[16:17]
	s_nop 0
	v_cvt_pk_bf16_f32 v16, v16, v17
	v_mul_f32_e32 v17, 0x3d372713, v30
	v_mul_f32_e32 v17, v30, v17
	v_fma_f32 v17, v30, v17, v30
	v_mul_f32_e32 v17, 0xbfcc422a, v17
	v_mul_f32_e32 v17, 0x3fb8aa3b, v17
	v_exp_f32_e32 v17, v17
	s_nop 0
	v_add_f32_e32 v17, 1.0, v17
	v_rcp_f32_e32 v20, v17
	v_mul_f32_e32 v17, 0x3d372713, v31
	v_mul_f32_e32 v17, v31, v17
	v_fma_f32 v17, v31, v17, v31
	v_mul_f32_e32 v17, 0xbfcc422a, v17
	v_mul_f32_e32 v17, 0x3fb8aa3b, v17
	v_exp_f32_e32 v17, v17
	s_nop 0
	v_add_f32_e32 v17, 1.0, v17
	v_rcp_f32_e32 v21, v17
	s_nop 0
	v_pk_mul_f32 v[20:21], v[30:31], v[20:21]
	s_nop 0
	v_cvt_pk_bf16_f32 v17, v20, v21
	global_store_dwordx2 v[18:19], v[16:17], off offset:16
	v_mul_f32_e32 v17, 0x3d372713, v0
	v_mul_f32_e32 v17, v0, v17
	v_fma_f32 v17, v0, v17, v0
	v_mul_f32_e32 v17, 0xbfcc422a, v17
	v_mul_f32_e32 v17, 0x3fb8aa3b, v17
	v_exp_f32_e32 v17, v17
	v_or_b32_e32 v16, 14, v70
	v_or_b32_e32 v70, 15, v70
	v_add_f32_e32 v17, 1.0, v17
	v_rcp_f32_e32 v18, v17
	v_mul_f32_e32 v17, 0x3d372713, v1
	v_mul_f32_e32 v17, v1, v17
	v_fma_f32 v17, v1, v17, v1
	v_mul_f32_e32 v17, 0xbfcc422a, v17
	v_mul_f32_e32 v17, 0x3fb8aa3b, v17
	v_exp_f32_e32 v17, v17
	s_nop 0
	v_add_f32_e32 v17, 1.0, v17
	v_rcp_f32_e32 v19, v17
	v_ashrrev_i32_e32 v17, 31, v16
	v_pk_mul_f32 v[0:1], v[0:1], v[18:19]
	s_nop 0
	v_cvt_pk_bf16_f32 v0, v0, v1
	v_mul_f32_e32 v1, 0x3d372713, v2
	v_mul_f32_e32 v1, v2, v1
	v_fma_f32 v1, v2, v1, v2
	v_mul_f32_e32 v1, 0xbfcc422a, v1
	v_mul_f32_e32 v1, 0x3fb8aa3b, v1
	v_exp_f32_e32 v1, v1
	s_nop 0
	v_add_f32_e32 v1, 1.0, v1
	v_rcp_f32_e32 v18, v1
	v_mul_f32_e32 v1, 0x3d372713, v3
	v_mul_f32_e32 v1, v3, v1
	v_fma_f32 v1, v3, v1, v3
	v_mul_f32_e32 v1, 0xbfcc422a, v1
	v_mul_f32_e32 v1, 0x3fb8aa3b, v1
	v_exp_f32_e32 v1, v1
	s_nop 0
	v_add_f32_e32 v1, 1.0, v1
	v_rcp_f32_e32 v19, v1
	s_nop 0
	v_pk_mul_f32 v[2:3], v[2:3], v[18:19]
	s_nop 0
	v_cvt_pk_bf16_f32 v1, v2, v3
	v_lshlrev_b64 v[2:3], 10, v[16:17]
	v_lshl_add_u64 v[2:3], s[18:19], 0, v[2:3]
	v_lshl_add_u64 v[2:3], v[2:3], 0, v[48:49]
	global_store_dwordx2 v[2:3], v[0:1], off
	v_mul_f32_e32 v0, 0x3d372713, v4
	v_mul_f32_e32 v1, 0x3d372713, v5
	v_mul_f32_e32 v0, v4, v0
	v_mul_f32_e32 v1, v5, v1
	v_fma_f32 v0, v4, v0, v4
	v_fma_f32 v1, v5, v1, v5
	v_mul_f32_e32 v0, 0xbfcc422a, v0
	v_mul_f32_e32 v1, 0xbfcc422a, v1
	v_mul_f32_e32 v0, 0x3fb8aa3b, v0
	v_mul_f32_e32 v1, 0x3fb8aa3b, v1
	v_exp_f32_e32 v0, v0
	v_exp_f32_e32 v1, v1
	s_mov_b64 s[18:19], exec
	v_add_f32_e32 v0, 1.0, v0
	v_add_f32_e32 v1, 1.0, v1
	v_rcp_f32_e32 v0, v0
	v_rcp_f32_e32 v1, v1
	s_nop 0
	v_pk_mul_f32 v[0:1], v[4:5], v[0:1]
	s_nop 0
	v_cvt_pk_bf16_f32 v0, v0, v1
	v_mul_f32_e32 v1, 0x3d372713, v6
	v_mul_f32_e32 v1, v6, v1
	v_fma_f32 v1, v6, v1, v6
	v_mul_f32_e32 v1, 0xbfcc422a, v1
	v_mul_f32_e32 v1, 0x3fb8aa3b, v1
	v_exp_f32_e32 v1, v1
	s_nop 0
	v_add_f32_e32 v1, 1.0, v1
	v_rcp_f32_e32 v4, v1
	v_mul_f32_e32 v1, 0x3d372713, v7
	v_mul_f32_e32 v1, v7, v1
	v_fma_f32 v1, v7, v1, v7
	v_mul_f32_e32 v1, 0xbfcc422a, v1
	v_mul_f32_e32 v1, 0x3fb8aa3b, v1
	v_exp_f32_e32 v1, v1
	s_nop 0
	v_add_f32_e32 v1, 1.0, v1
	v_rcp_f32_e32 v5, v1
	s_nop 0
	v_pk_mul_f32 v[4:5], v[6:7], v[4:5]
	s_nop 0
	v_cvt_pk_bf16_f32 v1, v4, v5
	global_store_dwordx2 v[2:3], v[0:1], off offset:16
	v_mul_f32_e32 v0, 0x3d372713, v8
	v_mul_f32_e32 v1, 0x3d372713, v9
	v_mul_f32_e32 v0, v8, v0
	v_mul_f32_e32 v1, v9, v1
	v_fma_f32 v0, v8, v0, v8
	v_fma_f32 v1, v9, v1, v9
	v_mul_f32_e32 v0, 0xbfcc422a, v0
	v_mul_f32_e32 v1, 0xbfcc422a, v1
	v_mul_f32_e32 v0, 0x3fb8aa3b, v0
	v_mul_f32_e32 v1, 0x3fb8aa3b, v1
	v_exp_f32_e32 v0, v0
	v_exp_f32_e32 v1, v1
	v_add_f32_e32 v0, 1.0, v0
	v_add_f32_e32 v1, 1.0, v1
	v_rcp_f32_e32 v0, v0
	v_rcp_f32_e32 v1, v1
	s_nop 0
	v_pk_mul_f32 v[0:1], v[8:9], v[0:1]
	s_nop 0
	v_cvt_pk_bf16_f32 v68, v0, v1
	v_mul_f32_e32 v0, 0x3d372713, v10
	v_mul_f32_e32 v1, 0x3d372713, v11
	v_mul_f32_e32 v0, v10, v0
	v_mul_f32_e32 v1, v11, v1
	v_fma_f32 v0, v10, v0, v10
	v_fma_f32 v1, v11, v1, v11
	v_mul_f32_e32 v0, 0xbfcc422a, v0
	v_mul_f32_e32 v1, 0xbfcc422a, v1
	v_mul_f32_e32 v0, 0x3fb8aa3b, v0
	v_mul_f32_e32 v1, 0x3fb8aa3b, v1
	v_exp_f32_e32 v0, v0
	v_exp_f32_e32 v1, v1
	v_add_f32_e32 v0, 1.0, v0
	v_add_f32_e32 v1, 1.0, v1
	v_rcp_f32_e32 v0, v0
	v_rcp_f32_e32 v1, v1
	s_nop 0
	v_pk_mul_f32 v[0:1], v[10:11], v[0:1]
	s_nop 0
	v_cvt_pk_bf16_f32 v69, v0, v1

.LBB0_1519:
	v_mov_b32_e32 v0, v102
	s_add_u32 s0, s3, s20
	v_and_b32_e32 v96, 31, v0
	v_or_b32_e32 v105, s54, v96
	s_movk_i32 s20, 0x81
	v_cmp_gt_i32_e32 vcc, s20, v105
	v_ashrrev_i32_e32 v104, 5, v0
	v_mov_b64_e32 v[0:1], s[6:7]
	v_cndmask_b32_e32 v100, 0, v105, vcc
	v_lshl_add_u32 v2, v100, 4, s27
	s_addc_u32 s1, s5, s21
	v_mad_i64_i32 v[0:1], s[20:21], v2, s44, v[0:1]
	v_lshlrev_b32_e32 v2, 3, v104
	v_ashrrev_i32_e32 v3, 31, v2
	s_lshl_b32 s20, s31, 5
	s_mov_b32 s21, s39
	v_lshl_add_u64 v[0:1], v[0:1], 0, s[20:21]
	v_lshlrev_b64 v[98:99], 1, v[2:3]
	v_lshl_add_u64 v[94:95], v[0:1], 0, v[98:99]
	s_mov_b64 s[100:101], 0x1ec00000
	v_lshl_add_u64 v[200:201], v[94:95], 0, s[100:101]
	global_load_dwordx4 v[124:127], v[200:201], off offset:3584
	s_mov_b64 s[100:101], 0x1ec03000
	v_lshl_add_u64 v[200:201], v[94:95], 0, s[100:101]
	global_load_dwordx4 v[148:151], v[200:201], off offset:3584
	s_mov_b64 s[100:101], 0x1ec06000
	v_lshl_add_u64 v[200:201], v[94:95], 0, s[100:101]
	global_load_dwordx4 v[164:167], v[200:201], off offset:3584
	s_mov_b64 s[100:101], 0x1ec09000
	v_lshl_add_u64 v[200:201], v[94:95], 0, s[100:101]
	global_load_dwordx4 v[180:183], v[200:201], off offset:3584
	s_mov_b64 s[100:101], 0x1ec0c000
	v_lshl_add_u64 v[200:201], v[94:95], 0, s[100:101]
	global_load_dwordx4 v[196:199], v[200:201], off offset:3584
	v_lshl_add_u64 v[0:1], s[0:1], 0, v[98:99]
	s_mov_b32 s0, 0x1ec00000
	v_add_co_u32_e64 v4, s[0:1], s0, v94
	v_lshlrev_b32_e32 v2, 9, v96
	s_nop 0
	v_addc_co_u32_e64 v5, s[0:1], 0, v95, s[0:1]
	v_mov_b32_e32 v3, v97
	v_lshl_add_u64 v[12:13], v[0:1], 0, v[2:3]
	global_load_dwordx4 v[120:123], v[12:13], off
	s_mov_b64 s[100:101], 0x8000
	v_lshl_add_u64 v[200:201], v[12:13], 0, s[100:101]
	global_load_dwordx4 v[128:131], v[200:201], off
	s_mov_b64 s[100:101], 0x18000
	v_lshl_add_u64 v[200:201], v[12:13], 0, s[100:101]
	global_load_dwordx4 v[136:139], v[200:201], off
	global_load_dwordx4 v[140:143], v[12:13], off offset:32
	s_mov_b32 s0, 0x8000
	v_add_co_u32_e64 v70, s[0:1], s0, v12
	s_nop 0
	v_addc_co_u32_e64 v71, s[0:1], 0, v13, s[0:1]
	global_load_dwordx4 v[144:147], v[70:71], off offset:32
	global_load_dwordx4 v[152:155], v[70:71], off offset:64
	global_load_dwordx4 v[176:179], v[70:71], off offset:96
	global_load_dwordx4 v[192:195], v[70:71], off offset:128
	v_add_co_u32_e64 v68, s[0:1], s75, v12
	v_ashrrev_i32_e32 v101, 31, v100
	s_nop 0
	v_addc_co_u32_e64 v69, s[0:1], 0, v13, s[0:1]
	global_load_dwordx4 v[132:135], v[68:69], off
	global_load_dwordx4 v[156:159], v[68:69], off offset:32
	global_load_dwordx4 v[168:171], v[68:69], off offset:64
	global_load_dwordx4 v[184:187], v[68:69], off offset:96
	s_mov_b32 s0, 0x18000
	s_nop 0
	v_add_co_u32_e64 v92, s[0:1], s0, v12
	s_lshl_b32 s38, s31, 4
	s_nop 0
	v_addc_co_u32_e64 v93, s[0:1], 0, v13, s[0:1]
	global_load_dwordx4 v[160:163], v[92:93], off offset:32
	global_load_dwordx4 v[172:175], v[92:93], off offset:64
	global_load_dwordx4 v[188:191], v[92:93], off offset:96
	s_mov_b32 s0, 0x1ec03000
	v_lshlrev_b32_e32 v96, 8, v96
	s_waitcnt vmcnt(19)
	v_cndmask_b32_e32 v127, 0, v127, vcc
	v_cndmask_b32_e32 v126, 0, v126, vcc
	v_cndmask_b32_e32 v125, 0, v125, vcc
	v_cndmask_b32_e32 v124, 0, v124, vcc
	s_nop 1
	s_waitcnt vmcnt(14)
	v_mfma_f32_32x32x16_bf16 v[48:63], v[120:123], v[124:127], 0
	global_load_dwordx4 v[120:123], v[68:69], off offset:128
	s_waitcnt vmcnt(14)
	v_mfma_f32_32x32x16_bf16 v[32:47], v[128:131], v[124:127], 0
	s_mov_b64 s[100:101], 0x1ec0f000
	v_lshl_add_u64 v[200:201], v[94:95], 0, s[100:101]
	global_load_dwordx4 v[128:131], v[200:201], off offset:3584
	v_add_co_u32_e64 v12, s[0:1], s0, v94
	s_nop 0
	v_addc_co_u32_e64 v13, s[0:1], 0, v95, s[0:1]
	s_mov_b32 s0, 0x1ec06000
	v_add_co_u32_e64 v84, s[0:1], s0, v94
	s_waitcnt vmcnt(8)
	v_mfma_f32_32x32x16_bf16 v[16:31], v[132:135], v[124:127], 0
	global_load_dwordx4 v[132:135], v[70:71], off offset:160
	v_addc_co_u32_e64 v85, s[0:1], 0, v95, s[0:1]
	s_mov_b32 s0, 0x1ec09000
	s_waitcnt vmcnt(21)
	v_cndmask_b32_e32 v151, 0, v151, vcc
	v_cndmask_b32_e32 v150, 0, v150, vcc
	v_cndmask_b32_e32 v149, 0, v149, vcc
	v_cndmask_b32_e32 v148, 0, v148, vcc
	s_waitcnt vmcnt(15)
	v_mfma_f32_32x32x16_bf16 v[0:15], v[136:139], v[124:127], 0
	global_load_dwordx4 v[124:127], v[92:93], off offset:128
	global_load_dwordx4 v[136:139], v[68:69], off offset:160
	s_nop 0
	s_waitcnt vmcnt(16)
	v_mfma_f32_32x32x16_bf16 v[48:63], v[140:143], v[148:151], v[48:63]
	global_load_dwordx4 v[140:143], v[92:93], off offset:160
	s_waitcnt vmcnt(16)
	v_mfma_f32_32x32x16_bf16 v[32:47], v[144:147], v[148:151], v[32:47]
	s_mov_b64 s[100:101], 0x1ec12000
	v_lshl_add_u64 v[200:201], v[94:95], 0, s[100:101]
	global_load_dwordx4 v[144:147], v[200:201], off offset:3584
	s_waitcnt vmcnt(12)
	v_mfma_f32_32x32x16_bf16 v[16:31], v[156:159], v[148:151], v[16:31]
	s_mov_b64 s[100:101], 0x1ec15000
	v_lshl_add_u64 v[200:201], v[94:95], 0, s[100:101]
	global_load_dwordx4 v[156:159], v[200:201], off offset:3584
	v_add_co_u32_e64 v84, s[0:1], s0, v94
	s_waitcnt vmcnt(25)
	v_cndmask_b32_e32 v167, 0, v167, vcc
	s_waitcnt vmcnt(10)
	v_mfma_f32_32x32x16_bf16 v[0:15], v[160:163], v[148:151], v[0:15]
	global_load_dwordx4 v[148:151], v[68:69], off offset:192
	global_load_dwordx4 v[160:163], v[68:69], off offset:224
	v_cndmask_b32_e32 v166, 0, v166, vcc
	v_cndmask_b32_e32 v165, 0, v165, vcc
	v_cndmask_b32_e32 v164, 0, v164, vcc
	v_addc_co_u32_e64 v85, s[0:1], 0, v95, s[0:1]
	s_nop 0
	s_waitcnt vmcnt(19)
	v_mfma_f32_32x32x16_bf16 v[32:47], v[152:155], v[164:167], v[32:47]
	global_load_dwordx4 v[152:155], v[92:93], off offset:192
	s_mov_b32 s0, 0x1ec0c000
	s_waitcnt vmcnt(15)
	v_mfma_f32_32x32x16_bf16 v[16:31], v[168:171], v[164:167], v[16:31]
	s_mov_b64 s[100:101], 0x1ec18000
	v_lshl_add_u64 v[200:201], v[94:95], 0, s[100:101]
	global_load_dwordx4 v[168:171], v[200:201], off offset:3584
	v_add_co_u32_e64 v84, s[0:1], s0, v94
	s_waitcnt vmcnt(28)
	v_cndmask_b32_e32 v183, 0, v183, vcc
	s_waitcnt vmcnt(13)
	v_mfma_f32_32x32x16_bf16 v[0:15], v[172:175], v[164:167], v[0:15]
	global_load_dwordx4 v[164:167], v[92:93], off offset:224
	global_load_dwordx4 v[172:175], v[68:69], off offset:256
	v_cndmask_b32_e32 v182, 0, v182, vcc
	v_cndmask_b32_e32 v181, 0, v181, vcc
	v_cndmask_b32_e32 v180, 0, v180, vcc
	v_addc_co_u32_e64 v85, s[0:1], 0, v95, s[0:1]
	s_nop 0
	s_waitcnt vmcnt(22)
	v_mfma_f32_32x32x16_bf16 v[32:47], v[176:179], v[180:183], v[32:47]
	global_load_dwordx4 v[176:179], v[92:93], off offset:256
	s_mov_b32 s0, 0x1ec0f000
	s_waitcnt vmcnt(18)
	v_mfma_f32_32x32x16_bf16 v[16:31], v[184:187], v[180:183], v[16:31]
	global_load_dwordx4 v[184:187], v[68:69], off offset:288
	s_waitcnt vmcnt(16)
	v_mfma_f32_32x32x16_bf16 v[0:15], v[188:191], v[180:183], v[0:15]
	global_load_dwordx4 v[180:183], v[92:93], off offset:288
	s_mov_b64 s[100:101], 0x1ec1b000
	v_lshl_add_u64 v[200:201], v[94:95], 0, s[100:101]
	global_load_dwordx4 v[188:191], v[200:201], off offset:3584
	s_waitcnt vmcnt(33)
	v_cndmask_b32_e32 v199, 0, v199, vcc
	v_cndmask_b32_e32 v198, 0, v198, vcc
	v_cndmask_b32_e32 v197, 0, v197, vcc
	v_cndmask_b32_e32 v196, 0, v196, vcc
	s_nop 0
	s_waitcnt vmcnt(17)
	v_mfma_f32_32x32x16_bf16 v[16:31], v[120:123], v[196:199], v[16:31]
	s_mov_b64 s[100:101], 0x1ec21000
	v_lshl_add_u64 v[200:201], v[94:95], 0, s[100:101]
	global_load_dwordx4 v[120:123], v[200:201], off offset:3584
	v_add_co_u32_e64 v72, s[0:1], s0, v94
	s_nop 1
	v_addc_co_u32_e64 v73, s[0:1], 0, v95, s[0:1]
	s_mov_b32 s0, 0x1ec12000
	s_waitcnt vmcnt(26)
	v_mfma_f32_32x32x16_bf16 v[32:47], v[192:195], v[196:199], v[32:47]
	s_mov_b64 s[100:101], 0x1ec1e000
	v_lshl_add_u64 v[200:201], v[94:95], 0, s[100:101]
	global_load_dwordx4 v[192:195], v[200:201], off offset:3584
	s_nop 0
	s_waitcnt vmcnt(18)
	v_cndmask_b32_e32 v131, 0, v131, vcc
	s_waitcnt vmcnt(16)
	v_mfma_f32_32x32x16_bf16 v[0:15], v[124:127], v[196:199], v[0:15]
	global_load_dwordx4 v[196:199], v[92:93], off offset:320
	global_load_dwordx4 v[124:127], v[92:93], off offset:352
	v_cndmask_b32_e32 v130, 0, v130, vcc
	v_cndmask_b32_e32 v129, 0, v129, vcc
	v_cndmask_b32_e32 v128, 0, v128, vcc
	s_nop 0
	s_waitcnt vmcnt(17)
	v_mfma_f32_32x32x16_bf16 v[16:31], v[136:139], v[128:131], v[16:31]
	s_mov_b64 s[100:101], 0x1ec27000
	v_lshl_add_u64 v[200:201], v[94:95], 0, s[100:101]
	global_load_dwordx4 v[136:139], v[200:201], off offset:3584
	v_add_co_u32_e64 v64, s[0:1], s0, v94
	s_nop 1
	v_addc_co_u32_e64 v65, s[0:1], 0, v95, s[0:1]
	s_mov_b32 s0, 0x1ec15000
	s_waitcnt vmcnt(20)
	v_mfma_f32_32x32x16_bf16 v[32:47], v[132:135], v[128:131], v[32:47]
	global_load_dwordx4 v[132:135], v[92:93], off offset:384
	s_nop 0
	s_waitcnt vmcnt(17)
	v_cndmask_b32_e32 v147, 0, v147, vcc
	s_waitcnt vmcnt(18)
	v_mfma_f32_32x32x16_bf16 v[0:15], v[140:143], v[128:131], v[0:15]
	s_mov_b64 s[100:101], 0x1ec24000
	v_lshl_add_u64 v[200:201], v[94:95], 0, s[100:101]
	global_load_dwordx4 v[128:131], v[200:201], off offset:3584
	global_load_dwordx4 v[140:143], v[92:93], off offset:416
	v_add_co_u32_e64 v74, s[0:1], s0, v94
	v_cndmask_b32_e32 v146, 0, v146, vcc
	v_cndmask_b32_e32 v145, 0, v145, vcc
	v_cndmask_b32_e32 v144, 0, v144, vcc
	v_addc_co_u32_e64 v75, s[0:1], 0, v95, s[0:1]
	s_waitcnt vmcnt(17)
	v_mfma_f32_32x32x16_bf16 v[16:31], v[148:151], v[144:147], v[16:31]
	s_nop 0
	s_mov_b32 s0, 0x1ec18000
	s_waitcnt vmcnt(18)
	v_cndmask_b32_e32 v159, 0, v159, vcc
	s_waitcnt vmcnt(15)
	v_mfma_f32_32x32x16_bf16 v[0:15], v[152:155], v[144:147], v[0:15]
	v_add_co_u32_e64 v64, s[0:1], s0, v94
	v_cndmask_b32_e32 v158, 0, v158, vcc
	s_nop 0
	v_addc_co_u32_e64 v65, s[0:1], 0, v95, s[0:1]
	v_cndmask_b32_e32 v157, 0, v157, vcc
	v_cndmask_b32_e32 v156, 0, v156, vcc
	s_nop 0
	s_waitcnt vmcnt(16)
	v_mfma_f32_32x32x16_bf16 v[16:31], v[160:163], v[156:159], v[16:31]
	s_mov_b32 s0, 0x1ec1b000
	v_add_co_u32_e64 v86, s[0:1], s0, v94
	s_nop 0
	v_addc_co_u32_e64 v87, s[0:1], 0, v95, s[0:1]
	s_waitcnt vmcnt(13)
	v_mfma_f32_32x32x16_bf16 v[0:15], v[164:167], v[156:159], v[0:15]
	s_mov_b32 s0, 0x1ec1e000
	s_waitcnt vmcnt(14)
	v_cndmask_b32_e32 v171, 0, v171, vcc
	v_cndmask_b32_e32 v170, 0, v170, vcc
	v_cndmask_b32_e32 v169, 0, v169, vcc
	v_cndmask_b32_e32 v168, 0, v168, vcc
	s_nop 0
	s_waitcnt vmcnt(12)
	v_mfma_f32_32x32x16_bf16 v[16:31], v[172:175], v[168:171], v[16:31]
	s_waitcnt vmcnt(11)
	v_mfma_f32_32x32x16_bf16 v[0:15], v[176:179], v[168:171], v[0:15]
	v_add_co_u32_e64 v64, s[0:1], s0, v94
	s_waitcnt vmcnt(8)
	v_cndmask_b32_e32 v67, 0, v191, vcc
	v_addc_co_u32_e64 v65, s[0:1], 0, v95, s[0:1]
	s_mov_b32 s0, 0x1ec21000
	v_add_co_u32_e64 v68, s[0:1], s0, v94
	v_cndmask_b32_e32 v66, 0, v190, vcc
	s_nop 0
	v_addc_co_u32_e64 v69, s[0:1], 0, v95, s[0:1]
	s_nop 0
	s_mov_b32 s0, 0x1ec24000
	v_add_co_u32_e64 v76, s[0:1], s0, v94
	v_cndmask_b32_e32 v65, 0, v189, vcc
	s_nop 0
	v_addc_co_u32_e64 v77, s[0:1], 0, v95, s[0:1]
	s_nop 0
	v_cndmask_b32_e32 v64, 0, v188, vcc
	s_mov_b32 s0, 0x1ec27000
	s_waitcnt vmcnt(6)
	v_cndmask_b32_e32 v195, 0, v195, vcc
	s_waitcnt vmcnt(10)
	v_mfma_f32_32x32x16_bf16 v[16:31], v[184:187], v[64:67], v[16:31]
	v_cndmask_b32_e32 v194, 0, v194, vcc
	v_cndmask_b32_e32 v193, 0, v193, vcc
	v_cndmask_b32_e32 v192, 0, v192, vcc
	s_waitcnt vmcnt(7)
	v_cndmask_b32_e32 v123, 0, v123, vcc
	v_cndmask_b32_e32 v122, 0, v122, vcc
	s_waitcnt vmcnt(9)
	v_mfma_f32_32x32x16_bf16 v[0:15], v[180:183], v[64:67], v[0:15]
	v_add_co_u32_e64 v64, s[0:1], s0, v94
	v_cndmask_b32_e32 v121, 0, v121, vcc
	s_nop 0
	v_addc_co_u32_e64 v65, s[0:1], 0, v95, s[0:1]
	s_nop 0
	v_cndmask_b32_e32 v120, 0, v120, vcc
	s_waitcnt vmcnt(5)
	v_mfma_f32_32x32x16_bf16 v[0:15], v[196:199], v[192:195], v[0:15]
	s_lshl_b64 s[0:1], s[16:17], 16
	s_lshl_b32 s16, s30, 5
	s_or_b32 s16, s16, s31
	s_add_u32 s0, s24, s0
	s_addc_u32 s1, s25, s1
	s_waitcnt vmcnt(3)
	v_cndmask_b32_e32 v139, 0, v139, vcc
	s_waitcnt vmcnt(4)
	v_mfma_f32_32x32x16_bf16 v[0:15], v[124:127], v[120:123], v[0:15]
	v_mov_b32_e32 v68, 0xa0
	v_mad_i64_i32 v[72:73], s[16:17], s16, v68, v[100:101]
	s_waitcnt vmcnt(1)
	v_cndmask_b32_e32 v71, 0, v131, vcc
	v_cndmask_b32_e32 v70, 0, v130, vcc
	v_cndmask_b32_e32 v69, 0, v129, vcc
	v_cndmask_b32_e32 v68, 0, v128, vcc
	v_cndmask_b32_e32 v138, 0, v138, vcc
	v_cndmask_b32_e32 v137, 0, v137, vcc
	s_waitcnt vmcnt(2)
	v_mfma_f32_32x32x16_bf16 v[0:15], v[132:135], v[68:71], v[0:15]
	v_lshlrev_b64 v[68:69], 8, v[72:73]
	v_cndmask_b32_e32 v136, 0, v136, vcc
	v_lshl_add_u64 v[68:69], s[12:13], 0, v[68:69]
	v_lshl_add_u64 v[72:73], v[68:69], 0, v[98:99]
	global_load_dwordx4 v[144:147], v[72:73], off
	global_load_dwordx4 v[164:167], v[72:73], off offset:32
	global_load_dwordx4 v[184:187], v[72:73], off offset:64
	global_load_dwordx4 v[124:127], v[72:73], off offset:96
	s_waitcnt vmcnt(4)
	v_mfma_f32_32x32x16_bf16 v[0:15], v[140:143], v[136:139], v[0:15]
	v_lshl_add_u64 v[64:65], s[0:1], 0, v[98:99]
	v_lshl_add_u64 v[70:71], v[64:65], 0, v[96:97]
	global_load_dwordx4 v[148:151], v[70:71], off
	global_load_dwordx4 v[168:171], v[70:71], off offset:32
	global_load_dwordx4 v[188:191], v[70:71], off offset:64
	global_load_dwordx4 v[128:131], v[70:71], off offset:96
	v_lshl_add_u64 v[82:83], v[64:65], 0, 32
	s_mov_b64 s[0:1], 0x60
	s_waitcnt vmcnt(7)
	v_cndmask_b32_e32 v81, 0, v147, vcc
	v_cndmask_b32_e32 v80, 0, v146, vcc
	v_or_b32_e32 v68, 0x4000, v96
	v_mov_b32_e32 v69, v97
	v_cndmask_b32_e32 v79, 0, v145, vcc
	v_cndmask_b32_e32 v78, 0, v144, vcc
	global_load_dwordx4 v[144:147], v[72:73], off offset:128
	v_lshl_add_u64 v[66:67], v[64:65], 0, v[68:69]
	global_load_dwordx4 v[152:155], v[66:67], off
	s_waitcnt vmcnt(5)
	v_mfma_f32_32x32x16_bf16 v[48:63], v[148:151], v[78:81], v[48:63]
	global_load_dwordx4 v[148:151], v[70:71], off offset:128
	v_or_b32_e32 v66, 0x8000, v96
	v_mov_b32_e32 v67, v97
	v_or_b32_e32 v96, 0xc000, v96
	s_waitcnt vmcnt(1)
	v_mfma_f32_32x32x16_bf16 v[32:47], v[152:155], v[78:81], v[32:47]
	v_lshl_add_u64 v[74:75], v[64:65], 0, v[66:67]
	global_load_dwordx4 v[156:159], v[74:75], off
	s_waitcnt vmcnt(0)
	v_mfma_f32_32x32x16_bf16 v[16:31], v[156:159], v[78:81], v[16:31]
	v_lshl_add_u64 v[74:75], v[64:65], 0, v[96:97]
	global_load_dwordx4 v[160:163], v[74:75], off
	s_waitcnt vmcnt(0)
	v_mfma_f32_32x32x16_bf16 v[0:15], v[160:163], v[78:81], v[0:15]
	s_waitcnt vmcnt(11)
	v_cndmask_b32_e32 v167, 0, v167, vcc
	v_cndmask_b32_e32 v166, 0, v166, vcc
	v_cndmask_b32_e32 v165, 0, v165, vcc
	v_cndmask_b32_e32 v164, 0, v164, vcc
	s_nop 0
	s_waitcnt vmcnt(7)
	v_mfma_f32_32x32x16_bf16 v[48:63], v[168:171], v[164:167], v[48:63]
	global_load_dwordx4 v[168:171], v[70:71], off offset:160
	v_lshl_add_u64 v[78:79], v[82:83], 0, v[68:69]
	global_load_dwordx4 v[172:175], v[78:79], off
	s_waitcnt vmcnt(0)
	v_mfma_f32_32x32x16_bf16 v[32:47], v[172:175], v[164:167], v[32:47]
	v_lshl_add_u64 v[78:79], v[82:83], 0, v[66:67]
	global_load_dwordx4 v[176:179], v[78:79], off
	s_waitcnt vmcnt(0)
	v_mfma_f32_32x32x16_bf16 v[16:31], v[176:179], v[164:167], v[16:31]
	v_lshl_add_u64 v[78:79], v[82:83], 0, v[96:97]
	global_load_dwordx4 v[180:183], v[78:79], off
	v_lshl_add_u64 v[82:83], v[64:65], 0, 64
	s_waitcnt vmcnt(0)
	v_mfma_f32_32x32x16_bf16 v[0:15], v[180:183], v[164:167], v[0:15]
	global_load_dwordx4 v[164:167], v[72:73], off offset:160
	s_waitcnt vmcnt(15)
	v_cndmask_b32_e32 v187, 0, v187, vcc
	v_cndmask_b32_e32 v186, 0, v186, vcc
	v_cndmask_b32_e32 v185, 0, v185, vcc
	v_cndmask_b32_e32 v184, 0, v184, vcc
	s_nop 0
	s_waitcnt vmcnt(11)
	v_mfma_f32_32x32x16_bf16 v[48:63], v[188:191], v[184:187], v[48:63]
	global_load_dwordx4 v[188:191], v[70:71], off offset:192
	v_lshl_add_u64 v[78:79], v[82:83], 0, v[68:69]
	global_load_dwordx4 v[192:195], v[78:79], off
	s_waitcnt vmcnt(0)
	v_mfma_f32_32x32x16_bf16 v[32:47], v[192:195], v[184:187], v[32:47]
	v_lshl_add_u64 v[78:79], v[82:83], 0, v[66:67]
	global_load_dwordx4 v[196:199], v[78:79], off
	s_waitcnt vmcnt(0)
	v_mfma_f32_32x32x16_bf16 v[16:31], v[196:199], v[184:187], v[16:31]
	v_lshl_add_u64 v[78:79], v[82:83], 0, v[96:97]
	global_load_dwordx4 v[120:123], v[78:79], off
	v_lshl_add_u64 v[82:83], v[64:65], 0, s[0:1]
	s_mov_b64 s[0:1], 0xa0
	s_waitcnt vmcnt(0)
	v_mfma_f32_32x32x16_bf16 v[0:15], v[120:123], v[184:187], v[0:15]
	global_load_dwordx4 v[184:187], v[72:73], off offset:192
	s_waitcnt vmcnt(19)
	v_cndmask_b32_e32 v127, 0, v127, vcc
	v_cndmask_b32_e32 v126, 0, v126, vcc
	v_cndmask_b32_e32 v125, 0, v125, vcc
	v_cndmask_b32_e32 v124, 0, v124, vcc
	s_nop 0
	s_waitcnt vmcnt(15)
	v_mfma_f32_32x32x16_bf16 v[48:63], v[128:131], v[124:127], v[48:63]
	global_load_dwordx4 v[128:131], v[70:71], off offset:224
	v_lshl_add_u64 v[78:79], v[82:83], 0, v[68:69]
	global_load_dwordx4 v[132:135], v[78:79], off
	s_waitcnt vmcnt(0)
	v_mfma_f32_32x32x16_bf16 v[32:47], v[132:135], v[124:127], v[32:47]
	v_lshl_add_u64 v[78:79], v[82:83], 0, v[66:67]
	global_load_dwordx4 v[136:139], v[78:79], off
	s_waitcnt vmcnt(0)
	v_mfma_f32_32x32x16_bf16 v[16:31], v[136:139], v[124:127], v[16:31]
	v_lshl_add_u64 v[78:79], v[82:83], 0, v[96:97]
	global_load_dwordx4 v[140:143], v[78:79], off
	v_lshl_add_u64 v[82:83], v[64:65], 0, s[40:41]
	s_waitcnt vmcnt(0)
	v_mfma_f32_32x32x16_bf16 v[0:15], v[140:143], v[124:127], v[0:15]
	global_load_dwordx4 v[124:127], v[72:73], off offset:224
	s_waitcnt vmcnt(19)
	v_cndmask_b32_e32 v147, 0, v147, vcc
	v_cndmask_b32_e32 v146, 0, v146, vcc
	v_cndmask_b32_e32 v145, 0, v145, vcc
	v_cndmask_b32_e32 v144, 0, v144, vcc
	s_nop 0
	s_waitcnt vmcnt(17)
	v_mfma_f32_32x32x16_bf16 v[48:63], v[148:151], v[144:147], v[48:63]
	v_lshl_add_u64 v[78:79], v[82:83], 0, v[68:69]
	global_load_dwordx4 v[152:155], v[78:79], off
	s_waitcnt vmcnt(0)
	v_mfma_f32_32x32x16_bf16 v[32:47], v[152:155], v[144:147], v[32:47]
	v_lshl_add_u64 v[78:79], v[82:83], 0, v[66:67]
	global_load_dwordx4 v[156:159], v[78:79], off
	s_waitcnt vmcnt(0)
	v_mfma_f32_32x32x16_bf16 v[16:31], v[156:159], v[144:147], v[16:31]
	v_lshl_add_u64 v[78:79], v[82:83], 0, v[96:97]
	global_load_dwordx4 v[160:163], v[78:79], off
	v_lshl_add_u64 v[82:83], v[64:65], 0, s[0:1]
	s_mov_b64 s[0:1], 0xc0
	s_waitcnt vmcnt(0)
	v_mfma_f32_32x32x16_bf16 v[0:15], v[160:163], v[144:147], v[0:15]
	s_waitcnt vmcnt(13)
	v_cndmask_b32_e32 v167, 0, v167, vcc
	v_cndmask_b32_e32 v166, 0, v166, vcc
	v_cndmask_b32_e32 v165, 0, v165, vcc
	v_cndmask_b32_e32 v164, 0, v164, vcc
	s_nop 0
	s_waitcnt vmcnt(17)
	v_mfma_f32_32x32x16_bf16 v[48:63], v[168:171], v[164:167], v[48:63]
	v_lshl_add_u64 v[78:79], v[82:83], 0, v[68:69]
	global_load_dwordx4 v[172:175], v[78:79], off
	s_waitcnt vmcnt(0)
	v_mfma_f32_32x32x16_bf16 v[32:47], v[172:175], v[164:167], v[32:47]
	v_lshl_add_u64 v[78:79], v[82:83], 0, v[66:67]
	global_load_dwordx4 v[176:179], v[78:79], off
	s_waitcnt vmcnt(0)
	v_mfma_f32_32x32x16_bf16 v[16:31], v[176:179], v[164:167], v[16:31]
	v_lshl_add_u64 v[78:79], v[82:83], 0, v[96:97]
	global_load_dwordx4 v[180:183], v[78:79], off
	v_lshl_add_u64 v[82:83], v[64:65], 0, s[0:1]
	s_mov_b64 s[0:1], 0xe0
	s_waitcnt vmcnt(0)
	v_mfma_f32_32x32x16_bf16 v[0:15], v[180:183], v[164:167], v[0:15]
	s_waitcnt vmcnt(11)
	v_cndmask_b32_e32 v187, 0, v187, vcc
	v_cndmask_b32_e32 v186, 0, v186, vcc
	v_cndmask_b32_e32 v185, 0, v185, vcc
	v_cndmask_b32_e32 v184, 0, v184, vcc
	s_nop 0
	s_waitcnt vmcnt(15)
	v_mfma_f32_32x32x16_bf16 v[48:63], v[188:191], v[184:187], v[48:63]
	v_lshl_add_u64 v[78:79], v[82:83], 0, v[68:69]
	global_load_dwordx4 v[192:195], v[78:79], off
	s_waitcnt vmcnt(0)
	v_mfma_f32_32x32x16_bf16 v[32:47], v[192:195], v[184:187], v[32:47]
	v_lshl_add_u64 v[78:79], v[82:83], 0, v[66:67]
	global_load_dwordx4 v[196:199], v[78:79], off
	s_waitcnt vmcnt(0)
	v_mfma_f32_32x32x16_bf16 v[16:31], v[196:199], v[184:187], v[16:31]
	v_lshl_add_u64 v[78:79], v[82:83], 0, v[96:97]
	global_load_dwordx4 v[120:123], v[78:79], off
	s_waitcnt vmcnt(0)
	v_mfma_f32_32x32x16_bf16 v[0:15], v[120:123], v[184:187], v[0:15]
	v_lshl_add_u64 v[80:81], v[64:65], 0, s[0:1]
	v_lshl_add_u64 v[64:65], v[80:81], 0, v[68:69]
	global_load_dwordx4 v[132:135], v[64:65], off
	s_nop 0
	s_waitcnt vmcnt(10)
	v_cndmask_b32_e32 v127, 0, v127, vcc
	v_lshl_add_u64 v[64:65], v[80:81], 0, v[66:67]
	global_load_dwordx4 v[136:139], v[64:65], off
	v_cndmask_b32_e32 v126, 0, v126, vcc
	v_cndmask_b32_e32 v125, 0, v125, vcc
	v_cndmask_b32_e32 v124, 0, v124, vcc
	s_nop 0
	s_waitcnt vmcnt(0)
	v_mfma_f32_32x32x16_bf16 v[16:31], v[136:139], v[124:127], v[16:31]
	v_lshl_add_u64 v[64:65], v[80:81], 0, v[96:97]
	global_load_dwordx4 v[140:143], v[64:65], off
	s_waitcnt vmcnt(16)
	v_mfma_f32_32x32x16_bf16 v[48:63], v[128:131], v[124:127], v[48:63]
	s_waitcnt vmcnt(2)
	v_mfma_f32_32x32x16_bf16 v[32:47], v[132:135], v[124:127], v[32:47]
	s_waitcnt vmcnt(0)
	v_mfma_f32_32x32x16_bf16 v[0:15], v[140:143], v[124:127], v[0:15]
	s_and_saveexec_b64 s[0:1], vcc
	s_cbranch_execz .LBB0_1521
	s_nop 5
	v_mul_f32_e32 v65, 0x3d372713, v48
	v_mul_f32_e32 v65, v48, v65
	v_fma_f32 v65, v48, v65, v48
	v_mul_f32_e32 v65, 0xbfcc422a, v65
	v_mul_f32_e32 v65, 0x3fb8aa3b, v65
	v_exp_f32_e32 v65, v65
	v_lshl_add_u32 v70, v105, 4, s27
	s_lshl_b32 s16, s38, 1
	v_lshlrev_b32_e32 v64, 2, v104
	v_add_f32_e32 v65, 1.0, v65
	v_rcp_f32_e32 v66, v65
	v_mul_f32_e32 v65, 0x3d372713, v49
	v_mul_f32_e32 v65, v49, v65
	v_fma_f32 v65, v49, v65, v49
	v_mul_f32_e32 v65, 0xbfcc422a, v65
	v_mul_f32_e32 v65, 0x3fb8aa3b, v65
	v_exp_f32_e32 v65, v65
	s_add_u32 s16, s10, s16
	v_ashrrev_i32_e32 v71, 31, v70
	s_addc_u32 s17, s11, 0
	v_add_f32_e32 v65, 1.0, v65
	v_rcp_f32_e32 v67, v65
	v_ashrrev_i32_e32 v65, 31, v64
	s_or_b64 s[18:19], s[18:19], exec
	v_pk_mul_f32 v[48:49], v[48:49], v[66:67]
	s_nop 0
	v_cvt_pk_bf16_f32 v66, v48, v49
	v_mul_f32_e32 v48, 0x3d372713, v50
	v_mul_f32_e32 v49, 0x3d372713, v51
	v_mul_f32_e32 v48, v50, v48
	v_mul_f32_e32 v49, v51, v49
	v_fma_f32 v48, v50, v48, v50
	v_fma_f32 v49, v51, v49, v51
	v_mul_f32_e32 v48, 0xbfcc422a, v48
	v_mul_f32_e32 v49, 0xbfcc422a, v49
	v_mul_f32_e32 v48, 0x3fb8aa3b, v48
	v_mul_f32_e32 v49, 0x3fb8aa3b, v49
	v_exp_f32_e32 v48, v48
	v_exp_f32_e32 v49, v49
	v_add_f32_e32 v48, 1.0, v48
	v_add_f32_e32 v49, 1.0, v49
	v_rcp_f32_e32 v48, v48
	v_rcp_f32_e32 v49, v49
	s_nop 0
	v_pk_mul_f32 v[48:49], v[50:51], v[48:49]
	s_nop 0
	v_cvt_pk_bf16_f32 v67, v48, v49
	v_lshlrev_b64 v[48:49], 10, v[70:71]
	v_lshl_add_u64 v[50:51], s[16:17], 0, v[48:49]
	v_lshlrev_b64 v[48:49], 1, v[64:65]
	v_lshl_add_u64 v[50:51], v[50:51], 0, v[48:49]
	global_store_dwordx2 v[50:51], v[66:67], off
	v_mul_f32_e32 v67, 0x3d372713, v52
	v_mul_f32_e32 v67, v52, v67
	v_fma_f32 v67, v52, v67, v52
	v_mul_f32_e32 v67, 0xbfcc422a, v67
	v_mul_f32_e32 v67, 0x3fb8aa3b, v67
	v_exp_f32_e32 v67, v67
	v_add_u32_e32 v66, 8, v64
	v_add_f32_e32 v67, 1.0, v67
	v_rcp_f32_e32 v68, v67
	v_mul_f32_e32 v67, 0x3d372713, v53
	v_mul_f32_e32 v67, v53, v67
	v_fma_f32 v67, v53, v67, v53
	v_mul_f32_e32 v67, 0xbfcc422a, v67
	v_mul_f32_e32 v67, 0x3fb8aa3b, v67
	v_exp_f32_e32 v67, v67
	s_nop 0
	v_add_f32_e32 v67, 1.0, v67
	v_rcp_f32_e32 v69, v67
	v_ashrrev_i32_e32 v67, 31, v66
	v_pk_mul_f32 v[52:53], v[52:53], v[68:69]
	s_nop 0
	v_cvt_pk_bf16_f32 v52, v52, v53
	v_mul_f32_e32 v53, 0x3d372713, v54
	v_mul_f32_e32 v53, v54, v53
	v_fma_f32 v53, v54, v53, v54
	v_mul_f32_e32 v53, 0xbfcc422a, v53
	v_mul_f32_e32 v53, 0x3fb8aa3b, v53
	v_exp_f32_e32 v53, v53
	s_nop 0
	v_add_f32_e32 v53, 1.0, v53
	v_rcp_f32_e32 v68, v53
	v_mul_f32_e32 v53, 0x3d372713, v55
	v_mul_f32_e32 v53, v55, v53
	v_fma_f32 v53, v55, v53, v55
	v_mul_f32_e32 v53, 0xbfcc422a, v53
	v_mul_f32_e32 v53, 0x3fb8aa3b, v53
	v_exp_f32_e32 v53, v53
	s_nop 0
	v_add_f32_e32 v53, 1.0, v53
	v_rcp_f32_e32 v69, v53
	s_nop 0
	v_pk_mul_f32 v[54:55], v[54:55], v[68:69]
	s_nop 0
	v_cvt_pk_bf16_f32 v53, v54, v55
	global_store_dwordx2 v[50:51], v[52:53], off offset:16
	v_mul_f32_e32 v50, 0x3d372713, v56
	v_mul_f32_e32 v51, 0x3d372713, v57
	v_mul_f32_e32 v50, v56, v50
	v_mul_f32_e32 v51, v57, v51
	v_fma_f32 v50, v56, v50, v56
	v_fma_f32 v51, v57, v51, v57
	v_mul_f32_e32 v50, 0xbfcc422a, v50
	v_mul_f32_e32 v51, 0xbfcc422a, v51
	v_mul_f32_e32 v50, 0x3fb8aa3b, v50
	v_mul_f32_e32 v51, 0x3fb8aa3b, v51
	v_exp_f32_e32 v50, v50
	v_exp_f32_e32 v51, v51
	v_add_f32_e32 v50, 1.0, v50
	v_add_f32_e32 v51, 1.0, v51
	v_rcp_f32_e32 v50, v50
	v_rcp_f32_e32 v51, v51
	s_nop 0
	v_pk_mul_f32 v[50:51], v[56:57], v[50:51]
	s_nop 0
	v_cvt_pk_bf16_f32 v50, v50, v51
	v_mul_f32_e32 v51, 0x3d372713, v58
	v_mul_f32_e32 v51, v58, v51
	v_fma_f32 v51, v58, v51, v58
	v_mul_f32_e32 v51, 0xbfcc422a, v51
	v_mul_f32_e32 v51, 0x3fb8aa3b, v51
	v_exp_f32_e32 v51, v51
	s_nop 0
	v_add_f32_e32 v51, 1.0, v51
	v_rcp_f32_e32 v52, v51
	v_mul_f32_e32 v51, 0x3d372713, v59
	v_mul_f32_e32 v51, v59, v51
	v_fma_f32 v51, v59, v51, v59
	v_mul_f32_e32 v51, 0xbfcc422a, v51
	v_mul_f32_e32 v51, 0x3fb8aa3b, v51
	v_exp_f32_e32 v51, v51
	s_nop 0
	v_add_f32_e32 v51, 1.0, v51
	v_rcp_f32_e32 v53, v51
	s_nop 0
	v_pk_mul_f32 v[52:53], v[58:59], v[52:53]
	s_nop 0
	v_cvt_pk_bf16_f32 v51, v52, v53
	v_or_b32_e32 v52, 1, v70
	v_ashrrev_i32_e32 v53, 31, v52
	v_lshlrev_b64 v[52:53], 10, v[52:53]
	v_lshl_add_u64 v[52:53], s[16:17], 0, v[52:53]
	v_lshl_add_u64 v[52:53], v[52:53], 0, v[48:49]
	global_store_dwordx2 v[52:53], v[50:51], off
	v_mul_f32_e32 v50, 0x3d372713, v60
	v_mul_f32_e32 v51, 0x3d372713, v61
	v_mul_f32_e32 v50, v60, v50
	v_mul_f32_e32 v51, v61, v51
	v_fma_f32 v50, v60, v50, v60
	v_fma_f32 v51, v61, v51, v61
	v_mul_f32_e32 v50, 0xbfcc422a, v50
	v_mul_f32_e32 v51, 0xbfcc422a, v51
	v_mul_f32_e32 v50, 0x3fb8aa3b, v50
	v_mul_f32_e32 v51, 0x3fb8aa3b, v51
	v_exp_f32_e32 v50, v50
	v_exp_f32_e32 v51, v51
	v_add_f32_e32 v50, 1.0, v50
	v_add_f32_e32 v51, 1.0, v51
	v_rcp_f32_e32 v50, v50
	v_rcp_f32_e32 v51, v51
	s_nop 0
	v_pk_mul_f32 v[50:51], v[60:61], v[50:51]
	s_nop 0
	v_cvt_pk_bf16_f32 v50, v50, v51
	v_mul_f32_e32 v51, 0x3d372713, v62
	v_mul_f32_e32 v51, v62, v51
	v_fma_f32 v51, v62, v51, v62
	v_mul_f32_e32 v51, 0xbfcc422a, v51
	v_mul_f32_e32 v51, 0x3fb8aa3b, v51
	v_exp_f32_e32 v51, v51
	s_nop 0
	v_add_f32_e32 v51, 1.0, v51
	v_rcp_f32_e32 v54, v51
	v_mul_f32_e32 v51, 0x3d372713, v63
	v_mul_f32_e32 v51, v63, v51
	v_fma_f32 v51, v63, v51, v63
	v_mul_f32_e32 v51, 0xbfcc422a, v51
	v_mul_f32_e32 v51, 0x3fb8aa3b, v51
	v_exp_f32_e32 v51, v51
	s_nop 0
	v_add_f32_e32 v51, 1.0, v51
	v_rcp_f32_e32 v55, v51
	s_nop 0
	v_pk_mul_f32 v[54:55], v[62:63], v[54:55]
	s_nop 0
	v_cvt_pk_bf16_f32 v51, v54, v55
	global_store_dwordx2 v[52:53], v[50:51], off offset:16
	v_mul_f32_e32 v51, 0x3d372713, v32
	v_mul_f32_e32 v51, v32, v51
	v_fma_f32 v51, v32, v51, v32
	v_mul_f32_e32 v51, 0xbfcc422a, v51
	v_mul_f32_e32 v51, 0x3fb8aa3b, v51
	v_exp_f32_e32 v51, v51
	v_or_b32_e32 v50, 4, v70
	v_add_f32_e32 v51, 1.0, v51
	v_rcp_f32_e32 v52, v51
	v_mul_f32_e32 v51, 0x3d372713, v33
	v_mul_f32_e32 v51, v33, v51
	v_fma_f32 v51, v33, v51, v33
	v_mul_f32_e32 v51, 0xbfcc422a, v51
	v_mul_f32_e32 v51, 0x3fb8aa3b, v51
	v_exp_f32_e32 v51, v51
	s_nop 0
	v_add_f32_e32 v51, 1.0, v51
	v_rcp_f32_e32 v53, v51
	v_ashrrev_i32_e32 v51, 31, v50
	v_pk_mul_f32 v[32:33], v[32:33], v[52:53]
	s_nop 0
	v_cvt_pk_bf16_f32 v32, v32, v33
	v_mul_f32_e32 v33, 0x3d372713, v34
	v_mul_f32_e32 v33, v34, v33
	v_fma_f32 v33, v34, v33, v34
	v_mul_f32_e32 v33, 0xbfcc422a, v33
	v_mul_f32_e32 v33, 0x3fb8aa3b, v33
	v_exp_f32_e32 v33, v33
	s_nop 0
	v_add_f32_e32 v33, 1.0, v33
	v_rcp_f32_e32 v52, v33
	v_mul_f32_e32 v33, 0x3d372713, v35
	v_mul_f32_e32 v33, v35, v33
	v_fma_f32 v33, v35, v33, v35
	v_mul_f32_e32 v33, 0xbfcc422a, v33
	v_mul_f32_e32 v33, 0x3fb8aa3b, v33
	v_exp_f32_e32 v33, v33
	s_nop 0
	v_add_f32_e32 v33, 1.0, v33
	v_rcp_f32_e32 v53, v33
	s_nop 0
	v_pk_mul_f32 v[34:35], v[34:35], v[52:53]
	s_nop 0
	v_cvt_pk_bf16_f32 v33, v34, v35
	v_lshlrev_b64 v[34:35], 10, v[50:51]
	v_lshl_add_u64 v[34:35], s[16:17], 0, v[34:35]
	v_lshl_add_u64 v[34:35], v[34:35], 0, v[48:49]
	global_store_dwordx2 v[34:35], v[32:33], off
	v_mul_f32_e32 v32, 0x3d372713, v36
	v_mul_f32_e32 v33, 0x3d372713, v37
	v_mul_f32_e32 v32, v36, v32
	v_mul_f32_e32 v33, v37, v33
	v_fma_f32 v32, v36, v32, v36
	v_fma_f32 v33, v37, v33, v37
	v_mul_f32_e32 v32, 0xbfcc422a, v32
	v_mul_f32_e32 v33, 0xbfcc422a, v33
	v_mul_f32_e32 v32, 0x3fb8aa3b, v32
	v_mul_f32_e32 v33, 0x3fb8aa3b, v33
	v_exp_f32_e32 v32, v32
	v_exp_f32_e32 v33, v33
	v_add_f32_e32 v32, 1.0, v32
	v_add_f32_e32 v33, 1.0, v33
	v_rcp_f32_e32 v32, v32
	v_rcp_f32_e32 v33, v33
	s_nop 0
	v_pk_mul_f32 v[32:33], v[36:37], v[32:33]
	s_nop 0
	v_cvt_pk_bf16_f32 v32, v32, v33
	v_mul_f32_e32 v33, 0x3d372713, v38
	v_mul_f32_e32 v33, v38, v33
	v_fma_f32 v33, v38, v33, v38
	v_mul_f32_e32 v33, 0xbfcc422a, v33
	v_mul_f32_e32 v33, 0x3fb8aa3b, v33
	v_exp_f32_e32 v33, v33
	s_nop 0
	v_add_f32_e32 v33, 1.0, v33
	v_rcp_f32_e32 v36, v33
	v_mul_f32_e32 v33, 0x3d372713, v39
	v_mul_f32_e32 v33, v39, v33
	v_fma_f32 v33, v39, v33, v39
	v_mul_f32_e32 v33, 0xbfcc422a, v33
	v_mul_f32_e32 v33, 0x3fb8aa3b, v33
	v_exp_f32_e32 v33, v33
	s_nop 0
	v_add_f32_e32 v33, 1.0, v33
	v_rcp_f32_e32 v37, v33
	s_nop 0
	v_pk_mul_f32 v[36:37], v[38:39], v[36:37]
	s_nop 0
	v_cvt_pk_bf16_f32 v33, v36, v37
	global_store_dwordx2 v[34:35], v[32:33], off offset:16
	v_mul_f32_e32 v32, 0x3d372713, v40
	v_mul_f32_e32 v33, 0x3d372713, v41
	v_mul_f32_e32 v32, v40, v32
	v_mul_f32_e32 v33, v41, v33
	v_fma_f32 v32, v40, v32, v40
	v_fma_f32 v33, v41, v33, v41
	v_mul_f32_e32 v32, 0xbfcc422a, v32
	v_mul_f32_e32 v33, 0xbfcc422a, v33
	v_mul_f32_e32 v32, 0x3fb8aa3b, v32
	v_mul_f32_e32 v33, 0x3fb8aa3b, v33
	v_exp_f32_e32 v32, v32
	v_exp_f32_e32 v33, v33
	v_add_f32_e32 v32, 1.0, v32
	v_add_f32_e32 v33, 1.0, v33
	v_rcp_f32_e32 v32, v32
	v_rcp_f32_e32 v33, v33
	s_nop 0
	v_pk_mul_f32 v[32:33], v[40:41], v[32:33]
	s_nop 0
	v_cvt_pk_bf16_f32 v32, v32, v33
	v_mul_f32_e32 v33, 0x3d372713, v42
	v_mul_f32_e32 v33, v42, v33
	v_fma_f32 v33, v42, v33, v42
	v_mul_f32_e32 v33, 0xbfcc422a, v33
	v_mul_f32_e32 v33, 0x3fb8aa3b, v33
	v_exp_f32_e32 v33, v33
	s_nop 0
	v_add_f32_e32 v33, 1.0, v33
	v_rcp_f32_e32 v34, v33
	v_mul_f32_e32 v33, 0x3d372713, v43
	v_mul_f32_e32 v33, v43, v33
	v_fma_f32 v33, v43, v33, v43
	v_mul_f32_e32 v33, 0xbfcc422a, v33
	v_mul_f32_e32 v33, 0x3fb8aa3b, v33
	v_exp_f32_e32 v33, v33
	s_nop 0
	v_add_f32_e32 v33, 1.0, v33
	v_rcp_f32_e32 v35, v33
	s_nop 0
	v_pk_mul_f32 v[34:35], v[42:43], v[34:35]
	s_nop 0
	v_cvt_pk_bf16_f32 v33, v34, v35
	v_or_b32_e32 v34, 5, v70
	v_ashrrev_i32_e32 v35, 31, v34
	v_lshlrev_b64 v[34:35], 10, v[34:35]
	v_lshl_add_u64 v[34:35], s[16:17], 0, v[34:35]
	v_lshl_add_u64 v[34:35], v[34:35], 0, v[48:49]
	global_store_dwordx2 v[34:35], v[32:33], off
	v_mul_f32_e32 v32, 0x3d372713, v44
	v_mul_f32_e32 v33, 0x3d372713, v45
	v_mul_f32_e32 v32, v44, v32
	v_mul_f32_e32 v33, v45, v33
	v_fma_f32 v32, v44, v32, v44
	v_fma_f32 v33, v45, v33, v45
	v_mul_f32_e32 v32, 0xbfcc422a, v32
	v_mul_f32_e32 v33, 0xbfcc422a, v33
	v_mul_f32_e32 v32, 0x3fb8aa3b, v32
	v_mul_f32_e32 v33, 0x3fb8aa3b, v33
	v_exp_f32_e32 v32, v32
	v_exp_f32_e32 v33, v33
	v_add_f32_e32 v32, 1.0, v32
	v_add_f32_e32 v33, 1.0, v33
	v_rcp_f32_e32 v32, v32
	v_rcp_f32_e32 v33, v33
	s_nop 0
	v_pk_mul_f32 v[32:33], v[44:45], v[32:33]
	s_nop 0
	v_cvt_pk_bf16_f32 v32, v32, v33
	v_mul_f32_e32 v33, 0x3d372713, v46
	v_mul_f32_e32 v33, v46, v33
	v_fma_f32 v33, v46, v33, v46
	v_mul_f32_e32 v33, 0xbfcc422a, v33
	v_mul_f32_e32 v33, 0x3fb8aa3b, v33
	v_exp_f32_e32 v33, v33
	s_nop 0
	v_add_f32_e32 v33, 1.0, v33
	v_rcp_f32_e32 v36, v33
	v_mul_f32_e32 v33, 0x3d372713, v47
	v_mul_f32_e32 v33, v47, v33
	v_fma_f32 v33, v47, v33, v47
	v_mul_f32_e32 v33, 0xbfcc422a, v33
	v_mul_f32_e32 v33, 0x3fb8aa3b, v33
	v_exp_f32_e32 v33, v33
	s_nop 0
	v_add_f32_e32 v33, 1.0, v33
	v_rcp_f32_e32 v37, v33
	s_nop 0
	v_pk_mul_f32 v[36:37], v[46:47], v[36:37]
	s_nop 0
	v_cvt_pk_bf16_f32 v33, v36, v37
	global_store_dwordx2 v[34:35], v[32:33], off offset:16
	v_mul_f32_e32 v33, 0x3d372713, v16
	v_mul_f32_e32 v33, v16, v33
	v_fma_f32 v33, v16, v33, v16
	v_mul_f32_e32 v33, 0xbfcc422a, v33
	v_mul_f32_e32 v33, 0x3fb8aa3b, v33
	v_exp_f32_e32 v33, v33
	v_or_b32_e32 v32, 8, v70
	v_add_f32_e32 v33, 1.0, v33
	v_rcp_f32_e32 v34, v33
	v_mul_f32_e32 v33, 0x3d372713, v17
	v_mul_f32_e32 v33, v17, v33
	v_fma_f32 v33, v17, v33, v17
	v_mul_f32_e32 v33, 0xbfcc422a, v33
	v_mul_f32_e32 v33, 0x3fb8aa3b, v33
	v_exp_f32_e32 v33, v33
	s_nop 0
	v_add_f32_e32 v33, 1.0, v33
	v_rcp_f32_e32 v35, v33
	v_ashrrev_i32_e32 v33, 31, v32
	v_pk_mul_f32 v[16:17], v[16:17], v[34:35]
	s_nop 0
	v_cvt_pk_bf16_f32 v16, v16, v17
	v_mul_f32_e32 v17, 0x3d372713, v18
	v_mul_f32_e32 v17, v18, v17
	v_fma_f32 v17, v18, v17, v18
	v_mul_f32_e32 v17, 0xbfcc422a, v17
	v_mul_f32_e32 v17, 0x3fb8aa3b, v17
	v_exp_f32_e32 v17, v17
	s_nop 0
	v_add_f32_e32 v17, 1.0, v17
	v_rcp_f32_e32 v34, v17
	v_mul_f32_e32 v17, 0x3d372713, v19
	v_mul_f32_e32 v17, v19, v17
	v_fma_f32 v17, v19, v17, v19
	v_mul_f32_e32 v17, 0xbfcc422a, v17
	v_mul_f32_e32 v17, 0x3fb8aa3b, v17
	v_exp_f32_e32 v17, v17
	s_nop 0
	v_add_f32_e32 v17, 1.0, v17
	v_rcp_f32_e32 v35, v17
	s_nop 0
	v_pk_mul_f32 v[18:19], v[18:19], v[34:35]
	s_nop 0
	v_cvt_pk_bf16_f32 v17, v18, v19
	v_lshlrev_b64 v[18:19], 10, v[32:33]
	v_lshl_add_u64 v[18:19], s[16:17], 0, v[18:19]
	v_lshl_add_u64 v[18:19], v[18:19], 0, v[48:49]
	global_store_dwordx2 v[18:19], v[16:17], off
	v_mul_f32_e32 v16, 0x3d372713, v20
	v_mul_f32_e32 v17, 0x3d372713, v21
	v_mul_f32_e32 v16, v20, v16
	v_mul_f32_e32 v17, v21, v17
	v_fma_f32 v16, v20, v16, v20
	v_fma_f32 v17, v21, v17, v21
	v_mul_f32_e32 v16, 0xbfcc422a, v16
	v_mul_f32_e32 v17, 0xbfcc422a, v17
	v_mul_f32_e32 v16, 0x3fb8aa3b, v16
	v_mul_f32_e32 v17, 0x3fb8aa3b, v17
	v_exp_f32_e32 v16, v16
	v_exp_f32_e32 v17, v17
	v_add_f32_e32 v16, 1.0, v16
	v_add_f32_e32 v17, 1.0, v17
	v_rcp_f32_e32 v16, v16
	v_rcp_f32_e32 v17, v17
	s_nop 0
	v_pk_mul_f32 v[16:17], v[20:21], v[16:17]
	s_nop 0
	v_cvt_pk_bf16_f32 v16, v16, v17
	v_mul_f32_e32 v17, 0x3d372713, v22
	v_mul_f32_e32 v17, v22, v17
	v_fma_f32 v17, v22, v17, v22
	v_mul_f32_e32 v17, 0xbfcc422a, v17
	v_mul_f32_e32 v17, 0x3fb8aa3b, v17
	v_exp_f32_e32 v17, v17
	s_nop 0
	v_add_f32_e32 v17, 1.0, v17
	v_rcp_f32_e32 v20, v17
	v_mul_f32_e32 v17, 0x3d372713, v23
	v_mul_f32_e32 v17, v23, v17
	v_fma_f32 v17, v23, v17, v23
	v_mul_f32_e32 v17, 0xbfcc422a, v17
	v_mul_f32_e32 v17, 0x3fb8aa3b, v17
	v_exp_f32_e32 v17, v17
	s_nop 0
	v_add_f32_e32 v17, 1.0, v17
	v_rcp_f32_e32 v21, v17
	s_nop 0
	v_pk_mul_f32 v[20:21], v[22:23], v[20:21]
	s_nop 0
	v_cvt_pk_bf16_f32 v17, v20, v21
	global_store_dwordx2 v[18:19], v[16:17], off offset:16
	v_mul_f32_e32 v16, 0x3d372713, v24
	v_mul_f32_e32 v17, 0x3d372713, v25
	v_mul_f32_e32 v16, v24, v16
	v_mul_f32_e32 v17, v25, v17
	v_fma_f32 v16, v24, v16, v24
	v_fma_f32 v17, v25, v17, v25
	v_mul_f32_e32 v16, 0xbfcc422a, v16
	v_mul_f32_e32 v17, 0xbfcc422a, v17
	v_mul_f32_e32 v16, 0x3fb8aa3b, v16
	v_mul_f32_e32 v17, 0x3fb8aa3b, v17
	v_exp_f32_e32 v16, v16
	v_exp_f32_e32 v17, v17
	v_add_f32_e32 v16, 1.0, v16
	v_add_f32_e32 v17, 1.0, v17
	v_rcp_f32_e32 v16, v16
	v_rcp_f32_e32 v17, v17
	s_nop 0
	v_pk_mul_f32 v[16:17], v[24:25], v[16:17]
	s_nop 0
	v_cvt_pk_bf16_f32 v16, v16, v17
	v_mul_f32_e32 v17, 0x3d372713, v26
	v_mul_f32_e32 v17, v26, v17
	v_fma_f32 v17, v26, v17, v26
	v_mul_f32_e32 v17, 0xbfcc422a, v17
	v_mul_f32_e32 v17, 0x3fb8aa3b, v17
	v_exp_f32_e32 v17, v17
	s_nop 0
	v_add_f32_e32 v17, 1.0, v17
	v_rcp_f32_e32 v18, v17
	v_mul_f32_e32 v17, 0x3d372713, v27
	v_mul_f32_e32 v17, v27, v17
	v_fma_f32 v17, v27, v17, v27
	v_mul_f32_e32 v17, 0xbfcc422a, v17
	v_mul_f32_e32 v17, 0x3fb8aa3b, v17
	v_exp_f32_e32 v17, v17
	s_nop 0
	v_add_f32_e32 v17, 1.0, v17
	v_rcp_f32_e32 v19, v17
	s_nop 0
	v_pk_mul_f32 v[18:19], v[26:27], v[18:19]
	s_nop 0
	v_cvt_pk_bf16_f32 v17, v18, v19
	v_or_b32_e32 v18, 9, v70
	v_ashrrev_i32_e32 v19, 31, v18
	v_lshlrev_b64 v[18:19], 10, v[18:19]
	v_lshl_add_u64 v[18:19], s[16:17], 0, v[18:19]
	v_lshl_add_u64 v[18:19], v[18:19], 0, v[48:49]
	global_store_dwordx2 v[18:19], v[16:17], off
	v_mul_f32_e32 v16, 0x3d372713, v28
	v_mul_f32_e32 v17, 0x3d372713, v29
	v_mul_f32_e32 v16, v28, v16
	v_mul_f32_e32 v17, v29, v17
	v_fma_f32 v16, v28, v16, v28
	v_fma_f32 v17, v29, v17, v29
	v_mul_f32_e32 v16, 0xbfcc422a, v16
	v_mul_f32_e32 v17, 0xbfcc422a, v17
	v_mul_f32_e32 v16, 0x3fb8aa3b, v16
	v_mul_f32_e32 v17, 0x3fb8aa3b, v17
	v_exp_f32_e32 v16, v16
	v_exp_f32_e32 v17, v17
	v_add_f32_e32 v16, 1.0, v16
	v_add_f32_e32 v17, 1.0, v17
	v_rcp_f32_e32 v16, v16
	v_rcp_f32_e32 v17, v17
	s_nop 0
	v_pk_mul_f32 v[16:17], v[28:29], v[16:17]
	s_nop 0
	v_cvt_pk_bf16_f32 v16, v16, v17
	v_mul_f32_e32 v17, 0x3d372713, v30
	v_mul_f32_e32 v17, v30, v17
	v_fma_f32 v17, v30, v17, v30
	v_mul_f32_e32 v17, 0xbfcc422a, v17
	v_mul_f32_e32 v17, 0x3fb8aa3b, v17
	v_exp_f32_e32 v17, v17
	s_nop 0
	v_add_f32_e32 v17, 1.0, v17
	v_rcp_f32_e32 v20, v17
	v_mul_f32_e32 v17, 0x3d372713, v31
	v_mul_f32_e32 v17, v31, v17
	v_fma_f32 v17, v31, v17, v31
	v_mul_f32_e32 v17, 0xbfcc422a, v17
	v_mul_f32_e32 v17, 0x3fb8aa3b, v17
	v_exp_f32_e32 v17, v17
	s_nop 0
	v_add_f32_e32 v17, 1.0, v17
	v_rcp_f32_e32 v21, v17
	s_nop 0
	v_pk_mul_f32 v[20:21], v[30:31], v[20:21]
	s_nop 0
	v_cvt_pk_bf16_f32 v17, v20, v21
	global_store_dwordx2 v[18:19], v[16:17], off offset:16
	v_mul_f32_e32 v17, 0x3d372713, v0
	v_mul_f32_e32 v17, v0, v17
	v_fma_f32 v17, v0, v17, v0
	v_mul_f32_e32 v17, 0xbfcc422a, v17
	v_mul_f32_e32 v17, 0x3fb8aa3b, v17
	v_exp_f32_e32 v17, v17
	v_or_b32_e32 v16, 12, v70
	v_or_b32_e32 v70, 13, v70
	v_add_f32_e32 v17, 1.0, v17
	v_rcp_f32_e32 v18, v17
	v_mul_f32_e32 v17, 0x3d372713, v1
	v_mul_f32_e32 v17, v1, v17
	v_fma_f32 v17, v1, v17, v1
	v_mul_f32_e32 v17, 0xbfcc422a, v17
	v_mul_f32_e32 v17, 0x3fb8aa3b, v17
	v_exp_f32_e32 v17, v17
	s_nop 0
	v_add_f32_e32 v17, 1.0, v17
	v_rcp_f32_e32 v19, v17
	v_ashrrev_i32_e32 v17, 31, v16
	v_pk_mul_f32 v[0:1], v[0:1], v[18:19]
	s_nop 0
	v_cvt_pk_bf16_f32 v0, v0, v1
	v_mul_f32_e32 v1, 0x3d372713, v2
	v_mul_f32_e32 v1, v2, v1
	v_fma_f32 v1, v2, v1, v2
	v_mul_f32_e32 v1, 0xbfcc422a, v1
	v_mul_f32_e32 v1, 0x3fb8aa3b, v1
	v_exp_f32_e32 v1, v1
	s_nop 0
	v_add_f32_e32 v1, 1.0, v1
	v_rcp_f32_e32 v18, v1
	v_mul_f32_e32 v1, 0x3d372713, v3
	v_mul_f32_e32 v1, v3, v1
	v_fma_f32 v1, v3, v1, v3
	v_mul_f32_e32 v1, 0xbfcc422a, v1
	v_mul_f32_e32 v1, 0x3fb8aa3b, v1
	v_exp_f32_e32 v1, v1
	s_nop 0
	v_add_f32_e32 v1, 1.0, v1
	v_rcp_f32_e32 v19, v1
	s_nop 0
	v_pk_mul_f32 v[2:3], v[2:3], v[18:19]
	s_nop 0
	v_cvt_pk_bf16_f32 v1, v2, v3
	v_lshlrev_b64 v[2:3], 10, v[16:17]
	v_lshl_add_u64 v[2:3], s[16:17], 0, v[2:3]
	v_lshl_add_u64 v[2:3], v[2:3], 0, v[48:49]
	global_store_dwordx2 v[2:3], v[0:1], off
	v_mul_f32_e32 v0, 0x3d372713, v4
	v_mul_f32_e32 v1, 0x3d372713, v5
	v_mul_f32_e32 v0, v4, v0
	v_mul_f32_e32 v1, v5, v1
	v_fma_f32 v0, v4, v0, v4
	v_fma_f32 v1, v5, v1, v5
	v_mul_f32_e32 v0, 0xbfcc422a, v0
	v_mul_f32_e32 v1, 0xbfcc422a, v1
	v_mul_f32_e32 v0, 0x3fb8aa3b, v0
	v_mul_f32_e32 v1, 0x3fb8aa3b, v1
	v_exp_f32_e32 v0, v0
	v_exp_f32_e32 v1, v1
	v_add_f32_e32 v0, 1.0, v0
	v_add_f32_e32 v1, 1.0, v1
	v_rcp_f32_e32 v0, v0
	v_rcp_f32_e32 v1, v1
	s_nop 0
	v_pk_mul_f32 v[0:1], v[4:5], v[0:1]
	s_nop 0
	v_cvt_pk_bf16_f32 v0, v0, v1
	v_mul_f32_e32 v1, 0x3d372713, v6
	v_mul_f32_e32 v1, v6, v1
	v_fma_f32 v1, v6, v1, v6
	v_mul_f32_e32 v1, 0xbfcc422a, v1
	v_mul_f32_e32 v1, 0x3fb8aa3b, v1
	v_exp_f32_e32 v1, v1
	s_nop 0
	v_add_f32_e32 v1, 1.0, v1
	v_rcp_f32_e32 v4, v1
	v_mul_f32_e32 v1, 0x3d372713, v7
	v_mul_f32_e32 v1, v7, v1
	v_fma_f32 v1, v7, v1, v7
	v_mul_f32_e32 v1, 0xbfcc422a, v1
	v_mul_f32_e32 v1, 0x3fb8aa3b, v1
	v_exp_f32_e32 v1, v1
	s_nop 0
	v_add_f32_e32 v1, 1.0, v1
	v_rcp_f32_e32 v5, v1
	s_nop 0
	v_pk_mul_f32 v[4:5], v[6:7], v[4:5]
	s_nop 0
	v_cvt_pk_bf16_f32 v1, v4, v5
	global_store_dwordx2 v[2:3], v[0:1], off offset:16
	v_mul_f32_e32 v0, 0x3d372713, v8
	v_mul_f32_e32 v1, 0x3d372713, v9
	v_mul_f32_e32 v0, v8, v0
	v_mul_f32_e32 v1, v9, v1
	v_fma_f32 v0, v8, v0, v8
	v_fma_f32 v1, v9, v1, v9
	v_mul_f32_e32 v0, 0xbfcc422a, v0
	v_mul_f32_e32 v1, 0xbfcc422a, v1
	v_mul_f32_e32 v0, 0x3fb8aa3b, v0
	v_mul_f32_e32 v1, 0x3fb8aa3b, v1
	v_exp_f32_e32 v0, v0
	v_exp_f32_e32 v1, v1
	v_add_f32_e32 v0, 1.0, v0
	v_add_f32_e32 v1, 1.0, v1
	v_rcp_f32_e32 v0, v0
	v_rcp_f32_e32 v1, v1
	s_nop 0
	v_pk_mul_f32 v[0:1], v[8:9], v[0:1]
	s_nop 0
	v_cvt_pk_bf16_f32 v68, v0, v1
	v_mul_f32_e32 v0, 0x3d372713, v10
	v_mul_f32_e32 v1, 0x3d372713, v11
	v_mul_f32_e32 v0, v10, v0
	v_mul_f32_e32 v1, v11, v1
	v_fma_f32 v0, v10, v0, v10
	v_fma_f32 v1, v11, v1, v11
	v_mul_f32_e32 v0, 0xbfcc422a, v0
	v_mul_f32_e32 v1, 0xbfcc422a, v1
	v_mul_f32_e32 v0, 0x3fb8aa3b, v0
	v_mul_f32_e32 v1, 0x3fb8aa3b, v1
	v_exp_f32_e32 v0, v0
	v_exp_f32_e32 v1, v1
	v_add_f32_e32 v0, 1.0, v0
	v_add_f32_e32 v1, 1.0, v1
	v_rcp_f32_e32 v0, v0
	v_rcp_f32_e32 v1, v1
	s_nop 0
	v_pk_mul_f32 v[0:1], v[10:11], v[0:1]
	s_nop 0
	v_cvt_pk_bf16_f32 v69, v0, v1
